# attention window steps: bias, window mask and -m folded into the S MFMA accumulator init via 4 rotating register slots (fewer VALU per tile)
# speedup vs baseline: 1.0757x; 1.0040x over previous
.LBB0_465:
	v_add_f32_e32 v1, v1, v4
	v_mul_f32_e32 v4, 0x4f800000, v1
	v_cmp_gt_f32_e32 vcc, s70, v1
	v_add_f32_e32 v2, v2, v3
	v_mul_f32_e32 v3, 0x4f800000, v2
	v_cndmask_b32_e32 v1, v1, v4, vcc
	v_sqrt_f32_e32 v4, v1
	s_mul_i32 s82, s82, 0x88000
	s_lshl_b32 s81, s7, 1
	s_mov_b32 s42, s26
	v_add_u32_e32 v9, -1, v4
	v_fma_f32 v10, -v9, v4, v1
	v_cmp_ge_f32_e64 s[0:1], 0, v10
	v_add_u32_e32 v10, 1, v4
	s_mov_b32 s43, s27
	v_cndmask_b32_e64 v9, v4, v9, s[0:1]
	v_fma_f32 v4, -v10, v4, v1
	v_cmp_lt_f32_e64 s[0:1], 0, v4
	s_or_b32 s20, s5, 1
	s_and_b32 s4, s4, 15
	v_cndmask_b32_e64 v4, v9, v10, s[0:1]
	v_mul_f32_e32 v9, 0x37800000, v4
	v_cndmask_b32_e32 v4, v4, v9, vcc
	v_cmp_gt_f32_e32 vcc, s70, v2
	v_cmp_class_f32_e64 s[0:1], v1, v237
	s_lshl_b32 s4, s4, 10
	v_cndmask_b32_e32 v2, v2, v3, vcc
	v_sqrt_f32_e32 v3, v2
	v_cndmask_b32_e64 v1, v4, v1, s[0:1]
	s_waitcnt lgkmcnt(8)
	v_fma_f32 v1, v227, v1, v228
	v_mov_b32_e32 v224, 0
	v_add_u32_e32 v4, -1, v3
	v_fma_f32 v9, -v4, v3, v2
	v_cmp_ge_f32_e64 s[0:1], 0, v9
	v_add_u32_e32 v9, 1, v3
	s_mov_b32 s92, 0
	v_cndmask_b32_e64 v4, v3, v4, s[0:1]
	v_fma_f32 v3, -v9, v3, v2
	v_cmp_lt_f32_e64 s[0:1], 0, v3
	s_add_i32 s83, s83, 20
	s_add_i32 s84, s75, 4
	v_cndmask_b32_e64 v3, v4, v9, s[0:1]
	v_mul_f32_e32 v4, 0x37800000, v3
	v_cndmask_b32_e32 v3, v3, v4, vcc
	v_add_f32_e32 v4, v5, v6
	v_mul_f32_e32 v5, 0x4f800000, v4
	v_cmp_gt_f32_e32 vcc, s70, v4
	v_cmp_class_f32_e64 s[0:1], v2, v237
	v_mov_b32_e32 v225, v224
	v_cndmask_b32_e32 v4, v4, v5, vcc
	v_sqrt_f32_e32 v5, v4
	v_cndmask_b32_e64 v2, v3, v2, s[0:1]
	v_fma_f32 v2, v227, v2, v228
	v_max3_f32 v1, v1, 0, v2
	v_add_u32_e32 v2, -1, v5
	v_fma_f32 v3, -v2, v5, v4
	v_cmp_ge_f32_e64 s[0:1], 0, v3
	v_add_u32_e32 v3, 1, v5
	v_mov_b32_e32 v222, v224
	v_cndmask_b32_e64 v2, v5, v2, s[0:1]
	v_fma_f32 v5, -v3, v5, v4
	v_cmp_lt_f32_e64 s[0:1], 0, v5
	v_mov_b32_e32 v223, v224
	s_nop 0
	v_cndmask_b32_e64 v2, v2, v3, s[0:1]
	v_mul_f32_e32 v3, 0x37800000, v2
	s_lshl_b32 s0, s8, 1
	v_cndmask_b32_e32 v2, v2, v3, vcc
	v_cmp_class_f32_e32 vcc, v4, v237
	v_add_f32_e32 v3, v7, v8
	s_add_i32 s0, s0, s82
	v_cndmask_b32_e32 v2, v2, v4, vcc
	v_mul_f32_e32 v4, 0x4f800000, v3
	v_cmp_gt_f32_e32 vcc, s70, v3
	s_add_i32 s7, s0, 0x44000
	s_add_i32 s1, s0, 0x4c800
	v_cndmask_b32_e32 v3, v3, v4, vcc
	s_add_i32 s9, s0, 0x8800
	v_sqrt_f32_e32 v52, v3
	v_fma_f32 v2, v227, v2, v228
	v_add_u32_e32 v53, -1, v52
	v_fma_f32 v54, -v53, v52, v3
	v_cmp_ge_f32_e64 s[0:1], 0, v54
	v_add_u32_e32 v54, 1, v52
	s_nop 0
	v_cndmask_b32_e64 v53, v52, v53, s[0:1]
	v_fma_f32 v52, -v54, v52, v3
	v_cmp_lt_f32_e64 s[0:1], 0, v52
	s_nop 1
	v_cndmask_b32_e64 v52, v53, v54, s[0:1]
	v_mul_f32_e32 v53, 0x37800000, v52
	v_cndmask_b32_e32 v52, v52, v53, vcc
	v_cmp_class_f32_e32 vcc, v3, v237
	s_nop 1
	v_cndmask_b32_e32 v3, v52, v3, vcc
	v_fma_f32 v3, v227, v3, v228
	v_max3_f32 v239, v1, v2, v3
	v_add_u32_e32 v1, s59, v232
	v_sub_u32_e32 v1, v229, v1
	v_add_u32_e32 v2, 15, v1
	v_cmp_gt_u32_e64 s[0:1], 16, v2
	v_add_u32_e32 v2, 14, v1
	v_cmp_gt_u32_e64 s[6:7], 16, v2
	v_add_u32_e32 v2, 13, v1
	v_cmp_gt_u32_e64 s[8:9], 16, v2
	v_add_u32_e32 v2, 12, v1
	v_cmp_gt_u32_e64 s[10:11], 16, v2
	v_add_u32_e32 v2, 11, v1
	v_cmp_gt_u32_e64 s[12:13], 16, v2
	v_add_u32_e32 v2, 10, v1
	v_cmp_gt_u32_e64 s[14:15], 16, v2
	v_add_u32_e32 v2, 9, v1
	v_add_u32_e32 v1, 8, v1
	v_cmp_gt_u32_e64 s[18:19], 16, v1
	v_sub_u32_e64 v1, s20, 4 clamp
	v_cmp_gt_u32_e64 s[16:17], 16, v2
	v_readfirstlane_b32 s20, v1
	s_min_u32 s85, s20, 56
	s_or_b32 s20, s5, 2
	v_sub_u32_e64 v1, s20, 4 clamp
	s_or_b32 s5, s5, 3
	v_readfirstlane_b32 s20, v1
	v_sub_u32_e64 v1, s5, 4 clamp
	s_min_u32 s87, s20, 56
	v_readfirstlane_b32 s5, v1
	s_min_u32 s89, s5, 56
	s_lshl_b32 s5, s75, 8
	s_lshl_b32 s20, s59, 2
	s_or_b32 s5, s5, s20
	v_add_u32_e32 v1, 0x1000, v233
	v_add_u32_e32 v2, 0x1000, v235
	s_bfe_u32 s60, s59, 0x20003
	v_lshrrev_b32_e32 v85, 4, v226
	v_add_u32_e32 v86, s60, v85
	v_and_b32_e32 v87, 3, v86
	v_lshrrev_b32_e32 v86, 2, v86
	v_bfe_u32 v220, v226, 2, 2
	v_lshl_add_u32 v87, v220, 3, v87
	v_mul_u32_u24_e32 v87, 0x2200, v87
	v_lshl_add_u32 v87, v86, 6, v87
	v_and_b32_e32 v221, 3, v226
	v_lshl_add_u32 v234, v221, 4, v87
	v_lshl_add_u32 v87, v220, 3, v85
	v_mul_u32_u24_e32 v87, 0x2200, v87
	v_lshl_add_u32 v250, v221, 4, v87
	v_add_u32_e32 v251, 0x8800, v250
	v_add_u32_e32 v253, 0x44000, v250
	v_add_u32_e32 v254, 0x4c800, v250
	v_add_u32_e32 v3, 0x8800, v234
	v_add_u32_e32 v220, 0x44000, v234
	v_add_u32_e32 v221, 0x4c800, v234
	s_lshl_b32 s21, s77, 6
	s_or_b32 s21, s21, s59
	s_add_i32 s22, s21, 64
	s_lshl_b32 s60, s21, 10
	s_add_i32 s60, s60, s81
	s_lshr_b32 s61, s21, 5
	s_lshl_b32 s61, s61, 6
	s_add_i32 s61, s61, s82
	s_lshl_b32 s62, s22, 10
	s_add_i32 s62, s62, s81
	s_lshr_b32 s63, s22, 5
	s_lshl_b32 s63, s63, 6
	s_add_i32 s63, s63, s82
	buffer_load_dwordx4 v[176:179], v233, s[24:27], s60 offen
	buffer_load_dwordx4 v[172:175], v235, s[24:27], s60 offen
	buffer_load_dwordx4 v[168:171], v1, s[24:27], s60 offen
	buffer_load_dwordx4 v[164:167], v2, s[24:27], s60 offen
	buffer_load_dwordx4 v[32:35], v234, s[40:43], s61 offen
	buffer_load_dwordx4 v[28:31], v3, s[40:43], s61 offen
	buffer_load_dwordx4 v[24:27], v220, s[40:43], s61 offen
	buffer_load_dwordx4 v[20:23], v221, s[40:43], s61 offen
	buffer_load_dwordx4 v[48:51], v233, s[24:27], s62 offen
	buffer_load_dwordx4 v[44:47], v235, s[24:27], s62 offen
	buffer_load_dwordx4 v[40:43], v1, s[24:27], s62 offen
	buffer_load_dwordx4 v[36:39], v2, s[24:27], s62 offen
	buffer_load_dwordx4 v[16:19], v234, s[40:43], s63 offen
	buffer_load_dwordx4 v[12:15], v3, s[40:43], s63 offen
	buffer_load_dwordx4 v[8:11], v220, s[40:43], s63 offen
	buffer_load_dwordx4 v[4:7], v221, s[40:43], s63 offen
	s_sub_i32 s4, s5, s4
	v_add_u32_e32 v240, s4, v236
	ds_read_b128 v[132:135], v231 offset:0
	ds_read_b128 v[136:139], v231 offset:1024
	ds_read_b128 v[140:143], v231 offset:2048
	ds_read_b128 v[144:147], v231 offset:3072
	ds_read_b128 v[148:151], v231 offset:4096
	ds_read_b128 v[152:155], v231 offset:5120
	ds_read_b128 v[156:159], v231 offset:6144
	ds_read_b128 v[160:163], v231 offset:7168
	ds_read2_b32 v[204:205], v240 offset0:192 offset1:193
	ds_read2_b32 v[206:207], v240 offset0:194 offset1:195
	ds_read2_b32 v[208:209], v240 offset0:196 offset1:197
	ds_read2_b32 v[210:211], v240 offset0:198 offset1:199
	ds_read2_b32 v[80:81], v240 offset0:128 offset1:129
	ds_read2_b32 v[82:83], v240 offset0:130 offset1:131
	ds_read2_b32 v[84:85], v240 offset0:132 offset1:133
	ds_read2_b32 v[86:87], v240 offset0:134 offset1:135
	ds_read2_b32 v[180:181], v240 offset0:64 offset1:65
	ds_read2_b32 v[182:183], v240 offset0:66 offset1:67
	ds_read2_b32 v[184:185], v240 offset0:68 offset1:69
	ds_read2_b32 v[186:187], v240 offset0:70 offset1:71
	ds_read2_b32 v[212:213], v240 offset0:0 offset1:1
	ds_read2_b32 v[214:215], v240 offset0:2 offset1:3
	ds_read2_b32 v[242:243], v240 offset0:4 offset1:5
	ds_read2_b32 v[244:245], v240 offset0:6 offset1:7
	v_xor_b32_e32 v76, 0x80000000, v239
	v_xor_b32_e32 v77, 0x80000000, v239
	v_xor_b32_e32 v78, 0x80000000, v239
	v_xor_b32_e32 v79, 0x80000000, v239
	v_mov_b32_e32 v96, 0
	v_mov_b32_e32 v97, 0
	v_mov_b32_e32 v98, 0
	v_mov_b32_e32 v99, 0
	v_mov_b32_e32 v88, 0
	v_mov_b32_e32 v89, 0
	v_mov_b32_e32 v90, 0
	v_mov_b32_e32 v91, 0
	v_mov_b32_e32 v72, 0
	v_mov_b32_e32 v73, 0
	v_mov_b32_e32 v74, 0
	v_mov_b32_e32 v75, 0
	v_mov_b32_e32 v68, 0
	v_mov_b32_e32 v69, 0
	v_mov_b32_e32 v70, 0
	v_mov_b32_e32 v71, 0
	v_mov_b32_e32 v222, 0
	v_mov_b32_e32 v64, 0
	v_mov_b32_e32 v65, 0
	v_mov_b32_e32 v66, 0
	v_mov_b32_e32 v67, 0
	v_mov_b32_e32 v60, 0
	v_mov_b32_e32 v61, 0
	v_mov_b32_e32 v62, 0
	v_mov_b32_e32 v63, 0
	v_mov_b32_e32 v56, 0
	v_mov_b32_e32 v57, 0
	v_mov_b32_e32 v58, 0
	v_mov_b32_e32 v59, 0
	v_mov_b32_e32 v52, 0
	v_mov_b32_e32 v53, 0
	v_mov_b32_e32 v54, 0
	v_mov_b32_e32 v55, 0
	v_mov_b32_e32 v223, 0
	v_mov_b32_e32 v128, 0
	v_mov_b32_e32 v129, 0
	v_mov_b32_e32 v130, 0
	v_mov_b32_e32 v131, 0
	v_mov_b32_e32 v124, 0
	v_mov_b32_e32 v125, 0
	v_mov_b32_e32 v126, 0
	v_mov_b32_e32 v127, 0
	v_mov_b32_e32 v120, 0
	v_mov_b32_e32 v121, 0
	v_mov_b32_e32 v122, 0
	v_mov_b32_e32 v123, 0
	v_mov_b32_e32 v116, 0
	v_mov_b32_e32 v117, 0
	v_mov_b32_e32 v118, 0
	v_mov_b32_e32 v119, 0
	v_mov_b32_e32 v224, 0
	v_mov_b32_e32 v112, 0
	v_mov_b32_e32 v113, 0
	v_mov_b32_e32 v114, 0
	v_mov_b32_e32 v115, 0
	v_mov_b32_e32 v108, 0
	v_mov_b32_e32 v109, 0
	v_mov_b32_e32 v110, 0
	v_mov_b32_e32 v111, 0
	v_mov_b32_e32 v104, 0
	v_mov_b32_e32 v105, 0
	v_mov_b32_e32 v106, 0
	v_mov_b32_e32 v107, 0
	v_mov_b32_e32 v100, 0
	v_mov_b32_e32 v101, 0
	v_mov_b32_e32 v102, 0
	v_mov_b32_e32 v103, 0
	v_mov_b32_e32 v225, 0
	s_mov_b32 s92, 0
	s_waitcnt lgkmcnt(0)
	v_sub_f32_e32 v204, v204, v239
	v_sub_f32_e32 v205, v205, v239
	v_sub_f32_e32 v206, v206, v239
	v_sub_f32_e32 v207, v207, v239
	v_sub_f32_e32 v208, v208, v239
	v_sub_f32_e32 v209, v209, v239
	v_sub_f32_e32 v210, v210, v239
	v_sub_f32_e32 v211, v211, v239
	v_cndmask_b32_e64 v204, v238, v204, s[0:1]
	v_cndmask_b32_e64 v205, v238, v205, s[6:7]
	v_cndmask_b32_e64 v206, v238, v206, s[8:9]
	v_cndmask_b32_e64 v207, v238, v207, s[10:11]
	v_cndmask_b32_e64 v208, v238, v208, s[12:13]
	v_cndmask_b32_e64 v209, v238, v209, s[14:15]
	v_cndmask_b32_e64 v210, v238, v210, s[16:17]
	v_cndmask_b32_e64 v211, v238, v211, s[18:19]
	v_sub_f32_e32 v80, v80, v239
	v_sub_f32_e32 v81, v81, v239
	v_sub_f32_e32 v82, v82, v239
	v_sub_f32_e32 v83, v83, v239
	v_sub_f32_e32 v84, v84, v239
	v_sub_f32_e32 v85, v85, v239
	v_sub_f32_e32 v86, v86, v239
	v_sub_f32_e32 v87, v87, v239
	v_cndmask_b32_e64 v80, v238, v80, s[0:1]
	v_cndmask_b32_e64 v81, v238, v81, s[6:7]
	v_cndmask_b32_e64 v82, v238, v82, s[8:9]
	v_cndmask_b32_e64 v83, v238, v83, s[10:11]
	v_cndmask_b32_e64 v84, v238, v84, s[12:13]
	v_cndmask_b32_e64 v85, v238, v85, s[14:15]
	v_cndmask_b32_e64 v86, v238, v86, s[16:17]
	v_cndmask_b32_e64 v87, v238, v87, s[18:19]
	v_sub_f32_e32 v180, v180, v239
	v_sub_f32_e32 v181, v181, v239
	v_sub_f32_e32 v182, v182, v239
	v_sub_f32_e32 v183, v183, v239
	v_sub_f32_e32 v184, v184, v239
	v_sub_f32_e32 v185, v185, v239
	v_sub_f32_e32 v186, v186, v239
	v_sub_f32_e32 v187, v187, v239
	v_cndmask_b32_e64 v180, v238, v180, s[0:1]
	v_cndmask_b32_e64 v181, v238, v181, s[6:7]
	v_cndmask_b32_e64 v182, v238, v182, s[8:9]
	v_cndmask_b32_e64 v183, v238, v183, s[10:11]
	v_cndmask_b32_e64 v184, v238, v184, s[12:13]
	v_cndmask_b32_e64 v185, v238, v185, s[14:15]
	v_cndmask_b32_e64 v186, v238, v186, s[16:17]
	v_cndmask_b32_e64 v187, v238, v187, s[18:19]
	v_sub_f32_e32 v212, v212, v239
	v_sub_f32_e32 v213, v213, v239
	v_sub_f32_e32 v214, v214, v239
	v_sub_f32_e32 v215, v215, v239
	v_sub_f32_e32 v242, v242, v239
	v_sub_f32_e32 v243, v243, v239
	v_sub_f32_e32 v244, v244, v239
	v_sub_f32_e32 v245, v245, v239
	v_cndmask_b32_e64 v212, v238, v212, s[0:1]
	v_cndmask_b32_e64 v213, v238, v213, s[6:7]
	v_cndmask_b32_e64 v214, v238, v214, s[8:9]
	v_cndmask_b32_e64 v215, v238, v215, s[10:11]
	v_cndmask_b32_e64 v242, v238, v242, s[12:13]
	v_cndmask_b32_e64 v243, v238, v243, s[14:15]
	v_cndmask_b32_e64 v244, v238, v244, s[16:17]
	v_cndmask_b32_e64 v245, v238, v245, s[18:19]
	v_add_u32_e32 v240, 0x400, v240
	s_cmp_eq_u32 s76, 8
	s_cbranch_scc1 .Latt_n8
	s_add_i32 s20, s92, 2
	s_min_i32 s20, s20, s80
	s_add_i32 s21, s20, s77
	s_lshl_b32 s21, s21, 6
	s_or_b32 s21, s21, s59
	s_sub_i32 s22, s20, s76
	s_lshl_b32 s22, s22, 5
	s_addk_i32 s22, 0x1000
	s_cmp_lt_i32 s20, s76
	s_cselect_b32 s60, 1, 0
	s_cselect_b32 s20, s21, s22
	s_lshl_b32 s23, s20, 10
	s_add_i32 s23, s23, s81
	s_lshr_b32 s33, s20, 5
	s_lshl_b32 s33, s33, 6
	s_add_i32 s33, s33, s82
	s_waitcnt vmcnt(12)
	ds_read2_b32 v[212:213], v240 offset0:0 offset1:1
	ds_read2_b32 v[214:215], v240 offset0:2 offset1:3
	ds_read2_b32 v[242:243], v240 offset0:4 offset1:5
	ds_read2_b32 v[244:245], v240 offset0:6 offset1:7
	v_mfma_f32_16x16x32_bf16 v[188:191], v[176:179], v[132:135], v[204:207]
	v_mfma_f32_16x16x32_bf16 v[192:195], v[168:171], v[132:135], v[208:211]
	v_mfma_f32_16x16x32_bf16 v[188:191], v[172:175], v[136:139], v[188:191]
	v_mfma_f32_16x16x32_bf16 v[192:195], v[164:167], v[136:139], v[192:195]
	buffer_load_dwordx4 v[176:179], v233, s[24:27], s23 offen
	buffer_load_dwordx4 v[172:175], v235, s[24:27], s23 offen
	buffer_load_dwordx4 v[168:171], v1, s[24:27], s23 offen
	buffer_load_dwordx4 v[164:167], v2, s[24:27], s23 offen
	s_nop 2
	v_exp_f32_e32 v188, v188
	v_exp_f32_e32 v189, v189
	v_exp_f32_e32 v190, v190
	v_exp_f32_e32 v191, v191
	v_exp_f32_e32 v192, v192
	v_exp_f32_e32 v193, v193
	v_exp_f32_e32 v194, v194
	v_exp_f32_e32 v195, v195
	v_cvt_pk_bf16_f32 v246, v188, v189
	v_cvt_pk_bf16_f32 v247, v190, v191
	v_cvt_pk_bf16_f32 v248, v192, v193
	v_cvt_pk_bf16_f32 v249, v194, v195
	v_add_f32_e32 v188, v188, v189
	v_add_f32_e32 v190, v190, v191
	v_add_f32_e32 v192, v192, v193
	v_add_f32_e32 v194, v194, v195
	v_add_f32_e32 v188, v188, v190
	v_add_f32_e32 v192, v192, v194
	v_add_f32_e32 v188, v188, v192
	v_add_f32_e32 v222, v222, v188
	s_waitcnt lgkmcnt(0)
	s_waitcnt vmcnt(12)
	v_sub_f32_e32 v212, v212, v239
	v_sub_f32_e32 v213, v213, v239
	v_sub_f32_e32 v214, v214, v239
	v_mfma_f32_16x16x32_bf16 v[96:99], v[32:35], v[246:249], v[96:99]
	v_sub_f32_e32 v215, v215, v239
	v_sub_f32_e32 v242, v242, v239
	v_sub_f32_e32 v243, v243, v239
	v_mfma_f32_16x16x32_bf16 v[88:91], v[28:31], v[246:249], v[88:91]
	v_sub_f32_e32 v244, v244, v239
	v_sub_f32_e32 v245, v245, v239
	v_cndmask_b32_e64 v212, v238, v212, s[0:1]
	v_mfma_f32_16x16x32_bf16 v[72:75], v[24:27], v[246:249], v[72:75]
	v_cndmask_b32_e64 v213, v238, v213, s[6:7]
	v_cndmask_b32_e64 v214, v238, v214, s[8:9]
	v_cndmask_b32_e64 v215, v238, v215, s[10:11]
	v_mfma_f32_16x16x32_bf16 v[68:71], v[20:23], v[246:249], v[68:71]
	v_cndmask_b32_e64 v242, v238, v242, s[12:13]
	v_cndmask_b32_e64 v243, v238, v243, s[14:15]
	v_cndmask_b32_e64 v244, v238, v244, s[16:17]
	v_cndmask_b32_e64 v245, v238, v245, s[18:19]
	s_cmp_eq_u32 s60, 0
	s_cbranch_scc1 .Latt_vc1
	buffer_load_dwordx4 v[32:35], v234, s[40:43], s33 offen
	buffer_load_dwordx4 v[28:31], v3, s[40:43], s33 offen
	buffer_load_dwordx4 v[24:27], v220, s[40:43], s33 offen
	buffer_load_dwordx4 v[20:23], v221, s[40:43], s33 offen
	s_branch .Latt_ve1

.Latt_ve1:
	v_add_u32_e32 v240, 0x100, v240
	s_add_i32 s92, s92, 1
	s_add_i32 s20, s92, 2
	s_min_i32 s20, s20, s80
	s_add_i32 s21, s20, s77
	s_lshl_b32 s21, s21, 6
	s_or_b32 s21, s21, s59
	s_sub_i32 s22, s20, s76
	s_lshl_b32 s22, s22, 5
	s_addk_i32 s22, 0x1000
	s_cmp_lt_i32 s20, s76
	s_cselect_b32 s60, 1, 0
	s_cselect_b32 s20, s21, s22
	s_lshl_b32 s23, s20, 10
	s_add_i32 s23, s23, s81
	s_lshr_b32 s33, s20, 5
	s_lshl_b32 s33, s33, 6
	s_add_i32 s33, s33, s82
	s_waitcnt vmcnt(12)
	ds_read2_b32 v[180:181], v240 offset0:0 offset1:1
	ds_read2_b32 v[182:183], v240 offset0:2 offset1:3
	ds_read2_b32 v[184:185], v240 offset0:4 offset1:5
	ds_read2_b32 v[186:187], v240 offset0:6 offset1:7
	v_mfma_f32_16x16x32_bf16 v[188:191], v[48:51], v[140:143], v[204:207]
	v_mfma_f32_16x16x32_bf16 v[192:195], v[40:43], v[140:143], v[208:211]
	v_mfma_f32_16x16x32_bf16 v[188:191], v[44:47], v[144:147], v[188:191]
	v_mfma_f32_16x16x32_bf16 v[192:195], v[36:39], v[144:147], v[192:195]
	v_mfma_f32_16x16x32_bf16 v[196:199], v[48:51], v[132:135], v[212:215]
	v_mfma_f32_16x16x32_bf16 v[200:203], v[40:43], v[132:135], v[242:245]
	v_mfma_f32_16x16x32_bf16 v[196:199], v[44:47], v[136:139], v[196:199]
	v_mfma_f32_16x16x32_bf16 v[200:203], v[36:39], v[136:139], v[200:203]
	buffer_load_dwordx4 v[48:51], v233, s[24:27], s23 offen
	buffer_load_dwordx4 v[44:47], v235, s[24:27], s23 offen
	buffer_load_dwordx4 v[40:43], v1, s[24:27], s23 offen
	buffer_load_dwordx4 v[36:39], v2, s[24:27], s23 offen
	v_exp_f32_e32 v188, v188
	v_exp_f32_e32 v189, v189
	v_exp_f32_e32 v190, v190
	v_exp_f32_e32 v191, v191
	v_exp_f32_e32 v192, v192
	v_exp_f32_e32 v193, v193
	v_exp_f32_e32 v194, v194
	v_exp_f32_e32 v195, v195
	v_cvt_pk_bf16_f32 v246, v188, v189
	v_cvt_pk_bf16_f32 v247, v190, v191
	v_cvt_pk_bf16_f32 v248, v192, v193
	v_cvt_pk_bf16_f32 v249, v194, v195
	v_add_f32_e32 v188, v188, v189
	v_add_f32_e32 v190, v190, v191
	v_add_f32_e32 v192, v192, v193
	v_add_f32_e32 v194, v194, v195
	v_add_f32_e32 v188, v188, v190
	v_add_f32_e32 v192, v192, v194
	v_add_f32_e32 v188, v188, v192
	v_add_f32_e32 v223, v223, v188
	s_waitcnt vmcnt(12)
	v_exp_f32_e32 v196, v196
	v_exp_f32_e32 v197, v197
	v_exp_f32_e32 v198, v198
	v_exp_f32_e32 v199, v199
	v_mfma_f32_16x16x32_bf16 v[64:67], v[16:19], v[246:249], v[64:67]
	v_exp_f32_e32 v200, v200
	v_exp_f32_e32 v201, v201
	v_exp_f32_e32 v202, v202
	v_exp_f32_e32 v203, v203
	v_mfma_f32_16x16x32_bf16 v[60:63], v[12:15], v[246:249], v[60:63]
	v_cvt_pk_bf16_f32 v92, v196, v197
	v_cvt_pk_bf16_f32 v93, v198, v199
	v_cvt_pk_bf16_f32 v94, v200, v201
	v_cvt_pk_bf16_f32 v95, v202, v203
	v_mfma_f32_16x16x32_bf16 v[56:59], v[8:11], v[246:249], v[56:59]
	v_add_f32_e32 v196, v196, v197
	v_add_f32_e32 v198, v198, v199
	v_add_f32_e32 v200, v200, v201
	v_add_f32_e32 v202, v202, v203
	v_mfma_f32_16x16x32_bf16 v[52:55], v[4:7], v[246:249], v[52:55]
	v_add_f32_e32 v196, v196, v198
	v_add_f32_e32 v200, v200, v202
	v_add_f32_e32 v196, v196, v200
	v_add_f32_e32 v222, v222, v196
	s_waitcnt lgkmcnt(0)
	v_sub_f32_e32 v180, v180, v239
	v_sub_f32_e32 v181, v181, v239
	v_sub_f32_e32 v182, v182, v239
	v_mfma_f32_16x16x32_bf16 v[96:99], v[16:19], v[92:95], v[96:99]
	v_sub_f32_e32 v183, v183, v239
	v_sub_f32_e32 v184, v184, v239
	v_sub_f32_e32 v185, v185, v239
	v_mfma_f32_16x16x32_bf16 v[88:91], v[12:15], v[92:95], v[88:91]
	v_sub_f32_e32 v186, v186, v239
	v_sub_f32_e32 v187, v187, v239
	v_cndmask_b32_e64 v180, v238, v180, s[0:1]
	v_mfma_f32_16x16x32_bf16 v[72:75], v[8:11], v[92:95], v[72:75]
	v_cndmask_b32_e64 v181, v238, v181, s[6:7]
	v_cndmask_b32_e64 v182, v238, v182, s[8:9]
	v_cndmask_b32_e64 v183, v238, v183, s[10:11]
	v_mfma_f32_16x16x32_bf16 v[68:71], v[4:7], v[92:95], v[68:71]
	v_cndmask_b32_e64 v184, v238, v184, s[12:13]
	v_cndmask_b32_e64 v185, v238, v185, s[14:15]
	v_cndmask_b32_e64 v186, v238, v186, s[16:17]
	v_cndmask_b32_e64 v187, v238, v187, s[18:19]
	s_cmp_eq_u32 s60, 0
	s_cbranch_scc1 .Latt_vc2
	buffer_load_dwordx4 v[16:19], v234, s[40:43], s33 offen
	buffer_load_dwordx4 v[12:15], v3, s[40:43], s33 offen
	buffer_load_dwordx4 v[8:11], v220, s[40:43], s33 offen
	buffer_load_dwordx4 v[4:7], v221, s[40:43], s33 offen
	s_branch .Latt_ve2

.Latt_ve2:
	v_add_u32_e32 v240, 0x100, v240
	s_add_i32 s92, s92, 1
	s_add_i32 s20, s92, 2
	s_min_i32 s20, s20, s80
	s_add_i32 s21, s20, s77
	s_lshl_b32 s21, s21, 6
	s_or_b32 s21, s21, s59
	s_sub_i32 s22, s20, s76
	s_lshl_b32 s22, s22, 5
	s_addk_i32 s22, 0x1000
	s_cmp_lt_i32 s20, s76
	s_cselect_b32 s60, 1, 0
	s_cselect_b32 s20, s21, s22
	s_lshl_b32 s23, s20, 10
	s_add_i32 s23, s23, s81
	s_lshr_b32 s33, s20, 5
	s_lshl_b32 s33, s33, 6
	s_add_i32 s33, s33, s82
	s_waitcnt vmcnt(12)
	ds_read2_b32 v[80:81], v240 offset0:0 offset1:1
	ds_read2_b32 v[82:83], v240 offset0:2 offset1:3
	ds_read2_b32 v[84:85], v240 offset0:4 offset1:5
	ds_read2_b32 v[86:87], v240 offset0:6 offset1:7
	v_mfma_f32_16x16x32_bf16 v[188:191], v[176:179], v[148:151], v[204:207]
	v_mfma_f32_16x16x32_bf16 v[192:195], v[168:171], v[148:151], v[208:211]
	v_mfma_f32_16x16x32_bf16 v[188:191], v[172:175], v[152:155], v[188:191]
	v_mfma_f32_16x16x32_bf16 v[192:195], v[164:167], v[152:155], v[192:195]
	v_mfma_f32_16x16x32_bf16 v[196:199], v[176:179], v[140:143], v[212:215]
	v_mfma_f32_16x16x32_bf16 v[200:203], v[168:171], v[140:143], v[242:245]
	v_mfma_f32_16x16x32_bf16 v[196:199], v[172:175], v[144:147], v[196:199]
	v_mfma_f32_16x16x32_bf16 v[200:203], v[164:167], v[144:147], v[200:203]
	s_nop 2
	v_exp_f32_e32 v188, v188
	v_exp_f32_e32 v189, v189
	v_exp_f32_e32 v190, v190
	v_exp_f32_e32 v191, v191
	v_exp_f32_e32 v192, v192
	v_exp_f32_e32 v193, v193
	v_exp_f32_e32 v194, v194
	v_exp_f32_e32 v195, v195
	v_cvt_pk_bf16_f32 v246, v188, v189
	v_cvt_pk_bf16_f32 v247, v190, v191
	v_cvt_pk_bf16_f32 v248, v192, v193
	v_cvt_pk_bf16_f32 v249, v194, v195
	v_add_f32_e32 v188, v188, v189
	v_add_f32_e32 v190, v190, v191
	v_add_f32_e32 v192, v192, v193
	v_add_f32_e32 v194, v194, v195
	v_add_f32_e32 v188, v188, v190
	v_add_f32_e32 v192, v192, v194
	v_add_f32_e32 v188, v188, v192
	v_add_f32_e32 v224, v224, v188
	v_mfma_f32_16x16x32_bf16 v[188:191], v[176:179], v[132:135], v[180:183]
	v_mfma_f32_16x16x32_bf16 v[192:195], v[168:171], v[132:135], v[184:187]
	v_mfma_f32_16x16x32_bf16 v[188:191], v[172:175], v[136:139], v[188:191]
	v_mfma_f32_16x16x32_bf16 v[192:195], v[164:167], v[136:139], v[192:195]
	buffer_load_dwordx4 v[176:179], v233, s[24:27], s23 offen
	buffer_load_dwordx4 v[172:175], v235, s[24:27], s23 offen
	buffer_load_dwordx4 v[168:171], v1, s[24:27], s23 offen
	buffer_load_dwordx4 v[164:167], v2, s[24:27], s23 offen
	s_waitcnt vmcnt(12)
	v_exp_f32_e32 v196, v196
	v_exp_f32_e32 v197, v197
	v_exp_f32_e32 v198, v198
	v_exp_f32_e32 v199, v199
	v_mfma_f32_16x16x32_bf16 v[128:131], v[32:35], v[246:249], v[128:131]
	v_exp_f32_e32 v200, v200
	v_exp_f32_e32 v201, v201
	v_exp_f32_e32 v202, v202
	v_exp_f32_e32 v203, v203
	v_mfma_f32_16x16x32_bf16 v[124:127], v[28:31], v[246:249], v[124:127]
	v_cvt_pk_bf16_f32 v92, v196, v197
	v_cvt_pk_bf16_f32 v93, v198, v199
	v_cvt_pk_bf16_f32 v94, v200, v201
	v_cvt_pk_bf16_f32 v95, v202, v203
	v_mfma_f32_16x16x32_bf16 v[120:123], v[24:27], v[246:249], v[120:123]
	v_add_f32_e32 v196, v196, v197
	v_add_f32_e32 v198, v198, v199
	v_add_f32_e32 v200, v200, v201
	v_add_f32_e32 v202, v202, v203
	v_mfma_f32_16x16x32_bf16 v[116:119], v[20:23], v[246:249], v[116:119]
	v_add_f32_e32 v196, v196, v198
	v_add_f32_e32 v200, v200, v202
	v_add_f32_e32 v196, v196, v200
	v_add_f32_e32 v223, v223, v196
	v_exp_f32_e32 v188, v188
	v_exp_f32_e32 v189, v189
	v_exp_f32_e32 v190, v190
	v_exp_f32_e32 v191, v191
	v_mfma_f32_16x16x32_bf16 v[64:67], v[32:35], v[92:95], v[64:67]
	v_exp_f32_e32 v192, v192
	v_exp_f32_e32 v193, v193
	v_exp_f32_e32 v194, v194
	v_exp_f32_e32 v195, v195
	v_mfma_f32_16x16x32_bf16 v[60:63], v[28:31], v[92:95], v[60:63]
	v_cvt_pk_bf16_f32 v246, v188, v189
	v_cvt_pk_bf16_f32 v247, v190, v191
	v_cvt_pk_bf16_f32 v248, v192, v193
	v_cvt_pk_bf16_f32 v249, v194, v195
	v_mfma_f32_16x16x32_bf16 v[56:59], v[24:27], v[92:95], v[56:59]
	v_add_f32_e32 v188, v188, v189
	v_add_f32_e32 v190, v190, v191
	v_add_f32_e32 v192, v192, v193
	v_add_f32_e32 v194, v194, v195
	v_mfma_f32_16x16x32_bf16 v[52:55], v[20:23], v[92:95], v[52:55]
	v_add_f32_e32 v188, v188, v190
	v_add_f32_e32 v192, v192, v194
	v_add_f32_e32 v188, v188, v192
	v_add_f32_e32 v222, v222, v188
	s_waitcnt lgkmcnt(0)
	v_sub_f32_e32 v80, v80, v239
	v_sub_f32_e32 v81, v81, v239
	v_sub_f32_e32 v82, v82, v239
	v_mfma_f32_16x16x32_bf16 v[96:99], v[32:35], v[246:249], v[96:99]
	v_sub_f32_e32 v83, v83, v239
	v_sub_f32_e32 v84, v84, v239
	v_sub_f32_e32 v85, v85, v239
	v_mfma_f32_16x16x32_bf16 v[88:91], v[28:31], v[246:249], v[88:91]
	v_sub_f32_e32 v86, v86, v239
	v_sub_f32_e32 v87, v87, v239
	v_cndmask_b32_e64 v80, v238, v80, s[0:1]
	v_mfma_f32_16x16x32_bf16 v[72:75], v[24:27], v[246:249], v[72:75]
	v_cndmask_b32_e64 v81, v238, v81, s[6:7]
	v_cndmask_b32_e64 v82, v238, v82, s[8:9]
	v_cndmask_b32_e64 v83, v238, v83, s[10:11]
	v_mfma_f32_16x16x32_bf16 v[68:71], v[20:23], v[246:249], v[68:71]
	v_cndmask_b32_e64 v84, v238, v84, s[12:13]
	v_cndmask_b32_e64 v85, v238, v85, s[14:15]
	v_cndmask_b32_e64 v86, v238, v86, s[16:17]
	v_cndmask_b32_e64 v87, v238, v87, s[18:19]
	s_cmp_eq_u32 s60, 0
	s_cbranch_scc1 .Latt_vc3
	buffer_load_dwordx4 v[32:35], v234, s[40:43], s33 offen
	buffer_load_dwordx4 v[28:31], v3, s[40:43], s33 offen
	buffer_load_dwordx4 v[24:27], v220, s[40:43], s33 offen
	buffer_load_dwordx4 v[20:23], v221, s[40:43], s33 offen
	s_branch .Latt_ve3

.Latt_ve3:
	v_add_u32_e32 v240, 0x100, v240
	s_add_i32 s92, s92, 1
	s_add_i32 s20, s92, 2
	s_min_i32 s20, s20, s80
	s_add_i32 s21, s20, s77
	s_lshl_b32 s21, s21, 6
	s_or_b32 s21, s21, s59
	s_sub_i32 s22, s20, s76
	s_lshl_b32 s22, s22, 5
	s_addk_i32 s22, 0x1000
	s_cmp_lt_i32 s20, s76
	s_cselect_b32 s60, 1, 0
	s_cselect_b32 s20, s21, s22
	s_lshl_b32 s23, s20, 10
	s_add_i32 s23, s23, s81
	s_lshr_b32 s33, s20, 5
	s_lshl_b32 s33, s33, 6
	s_add_i32 s33, s33, s82
	s_waitcnt vmcnt(12)
	v_mfma_f32_16x16x32_bf16 v[188:191], v[48:51], v[156:159], v[204:207]
	v_mfma_f32_16x16x32_bf16 v[192:195], v[40:43], v[156:159], v[208:211]
	v_mfma_f32_16x16x32_bf16 v[188:191], v[44:47], v[160:163], v[188:191]
	v_mfma_f32_16x16x32_bf16 v[192:195], v[36:39], v[160:163], v[192:195]
	ds_read2_b32 v[204:205], v240 offset0:0 offset1:1
	ds_read2_b32 v[206:207], v240 offset0:2 offset1:3
	ds_read2_b32 v[208:209], v240 offset0:4 offset1:5
	ds_read2_b32 v[210:211], v240 offset0:6 offset1:7
	v_mfma_f32_16x16x32_bf16 v[196:199], v[48:51], v[148:151], v[212:215]
	v_mfma_f32_16x16x32_bf16 v[200:203], v[40:43], v[148:151], v[242:245]
	v_mfma_f32_16x16x32_bf16 v[196:199], v[44:47], v[152:155], v[196:199]
	v_mfma_f32_16x16x32_bf16 v[200:203], v[36:39], v[152:155], v[200:203]
	v_exp_f32_e32 v188, v188
	v_exp_f32_e32 v189, v189
	v_exp_f32_e32 v190, v190
	v_exp_f32_e32 v191, v191
	v_exp_f32_e32 v192, v192
	v_exp_f32_e32 v193, v193
	v_exp_f32_e32 v194, v194
	v_exp_f32_e32 v195, v195
	v_cvt_pk_bf16_f32 v246, v188, v189
	v_cvt_pk_bf16_f32 v247, v190, v191
	v_cvt_pk_bf16_f32 v248, v192, v193
	v_cvt_pk_bf16_f32 v249, v194, v195
	v_add_f32_e32 v188, v188, v189
	v_add_f32_e32 v190, v190, v191
	v_add_f32_e32 v192, v192, v193
	v_add_f32_e32 v194, v194, v195
	v_add_f32_e32 v188, v188, v190
	v_add_f32_e32 v192, v192, v194
	v_add_f32_e32 v188, v188, v192
	v_add_f32_e32 v225, v225, v188
	v_mfma_f32_16x16x32_bf16 v[188:191], v[48:51], v[140:143], v[180:183]
	v_mfma_f32_16x16x32_bf16 v[192:195], v[40:43], v[140:143], v[184:187]
	v_mfma_f32_16x16x32_bf16 v[188:191], v[44:47], v[144:147], v[188:191]
	v_mfma_f32_16x16x32_bf16 v[192:195], v[36:39], v[144:147], v[192:195]
	s_waitcnt vmcnt(8)
	v_exp_f32_e32 v196, v196
	v_exp_f32_e32 v197, v197
	v_exp_f32_e32 v198, v198
	v_exp_f32_e32 v199, v199
	v_mfma_f32_16x16x32_bf16 v[112:115], v[16:19], v[246:249], v[112:115]
	v_exp_f32_e32 v200, v200
	v_exp_f32_e32 v201, v201
	v_exp_f32_e32 v202, v202
	v_exp_f32_e32 v203, v203
	v_mfma_f32_16x16x32_bf16 v[108:111], v[12:15], v[246:249], v[108:111]
	v_cvt_pk_bf16_f32 v92, v196, v197
	v_cvt_pk_bf16_f32 v93, v198, v199
	v_cvt_pk_bf16_f32 v94, v200, v201
	v_cvt_pk_bf16_f32 v95, v202, v203
	v_mfma_f32_16x16x32_bf16 v[104:107], v[8:11], v[246:249], v[104:107]
	v_add_f32_e32 v196, v196, v197
	v_add_f32_e32 v198, v198, v199
	v_add_f32_e32 v200, v200, v201
	v_add_f32_e32 v202, v202, v203
	v_mfma_f32_16x16x32_bf16 v[100:103], v[4:7], v[246:249], v[100:103]
	v_add_f32_e32 v196, v196, v198
	v_add_f32_e32 v200, v200, v202
	v_add_f32_e32 v196, v196, v200
	v_add_f32_e32 v224, v224, v196
	v_mfma_f32_16x16x32_bf16 v[196:199], v[48:51], v[132:135], v[80:83]
	v_mfma_f32_16x16x32_bf16 v[200:203], v[40:43], v[132:135], v[84:87]
	v_mfma_f32_16x16x32_bf16 v[196:199], v[44:47], v[136:139], v[196:199]
	v_mfma_f32_16x16x32_bf16 v[200:203], v[36:39], v[136:139], v[200:203]
	buffer_load_dwordx4 v[48:51], v233, s[24:27], s23 offen
	buffer_load_dwordx4 v[44:47], v235, s[24:27], s23 offen
	buffer_load_dwordx4 v[40:43], v1, s[24:27], s23 offen
	buffer_load_dwordx4 v[36:39], v2, s[24:27], s23 offen
	v_exp_f32_e32 v188, v188
	v_exp_f32_e32 v189, v189
	v_exp_f32_e32 v190, v190
	v_exp_f32_e32 v191, v191
	v_mfma_f32_16x16x32_bf16 v[128:131], v[16:19], v[92:95], v[128:131]
	v_exp_f32_e32 v192, v192
	v_exp_f32_e32 v193, v193
	v_exp_f32_e32 v194, v194
	v_exp_f32_e32 v195, v195
	v_mfma_f32_16x16x32_bf16 v[124:127], v[12:15], v[92:95], v[124:127]
	v_cvt_pk_bf16_f32 v246, v188, v189
	v_cvt_pk_bf16_f32 v247, v190, v191
	v_cvt_pk_bf16_f32 v248, v192, v193
	v_cvt_pk_bf16_f32 v249, v194, v195
	v_mfma_f32_16x16x32_bf16 v[120:123], v[8:11], v[92:95], v[120:123]
	v_add_f32_e32 v188, v188, v189
	v_add_f32_e32 v190, v190, v191
	v_add_f32_e32 v192, v192, v193
	v_add_f32_e32 v194, v194, v195
	v_mfma_f32_16x16x32_bf16 v[116:119], v[4:7], v[92:95], v[116:119]
	v_add_f32_e32 v188, v188, v190
	v_add_f32_e32 v192, v192, v194
	v_add_f32_e32 v188, v188, v192
	v_add_f32_e32 v223, v223, v188
	v_exp_f32_e32 v196, v196
	v_exp_f32_e32 v197, v197
	v_exp_f32_e32 v198, v198
	v_exp_f32_e32 v199, v199
	v_mfma_f32_16x16x32_bf16 v[64:67], v[16:19], v[246:249], v[64:67]
	v_exp_f32_e32 v200, v200
	v_exp_f32_e32 v201, v201
	v_exp_f32_e32 v202, v202
	v_exp_f32_e32 v203, v203
	v_mfma_f32_16x16x32_bf16 v[60:63], v[12:15], v[246:249], v[60:63]
	v_cvt_pk_bf16_f32 v92, v196, v197
	v_cvt_pk_bf16_f32 v93, v198, v199
	v_cvt_pk_bf16_f32 v94, v200, v201
	v_cvt_pk_bf16_f32 v95, v202, v203
	v_mfma_f32_16x16x32_bf16 v[56:59], v[8:11], v[246:249], v[56:59]
	v_add_f32_e32 v196, v196, v197
	v_add_f32_e32 v198, v198, v199
	v_add_f32_e32 v200, v200, v201
	v_add_f32_e32 v202, v202, v203
	v_mfma_f32_16x16x32_bf16 v[52:55], v[4:7], v[246:249], v[52:55]
	v_add_f32_e32 v196, v196, v198
	v_add_f32_e32 v200, v200, v202
	v_add_f32_e32 v196, v196, v200
	v_add_f32_e32 v222, v222, v196
	s_waitcnt lgkmcnt(0)
	v_sub_f32_e32 v204, v204, v239
	v_sub_f32_e32 v205, v205, v239
	v_sub_f32_e32 v206, v206, v239
	v_mfma_f32_16x16x32_bf16 v[96:99], v[16:19], v[92:95], v[96:99]
	v_sub_f32_e32 v207, v207, v239
	v_sub_f32_e32 v208, v208, v239
	v_sub_f32_e32 v209, v209, v239
	v_mfma_f32_16x16x32_bf16 v[88:91], v[12:15], v[92:95], v[88:91]
	v_sub_f32_e32 v210, v210, v239
	v_sub_f32_e32 v211, v211, v239
	v_cndmask_b32_e64 v204, v238, v204, s[0:1]
	v_mfma_f32_16x16x32_bf16 v[72:75], v[8:11], v[92:95], v[72:75]
	v_cndmask_b32_e64 v205, v238, v205, s[6:7]
	v_cndmask_b32_e64 v206, v238, v206, s[8:9]
	v_cndmask_b32_e64 v207, v238, v207, s[10:11]
	v_mfma_f32_16x16x32_bf16 v[68:71], v[4:7], v[92:95], v[68:71]
	v_cndmask_b32_e64 v208, v238, v208, s[12:13]
	v_cndmask_b32_e64 v209, v238, v209, s[14:15]
	v_cndmask_b32_e64 v210, v238, v210, s[16:17]
	v_cndmask_b32_e64 v211, v238, v211, s[18:19]
	s_cmp_eq_u32 s60, 0
	s_cbranch_scc1 .Latt_vc4
	buffer_load_dwordx4 v[16:19], v234, s[40:43], s33 offen
	buffer_load_dwordx4 v[12:15], v3, s[40:43], s33 offen
	buffer_load_dwordx4 v[8:11], v220, s[40:43], s33 offen
	buffer_load_dwordx4 v[4:7], v221, s[40:43], s33 offen
	s_branch .Latt_ve4

.Latt_ve4:
	v_add_u32_e32 v240, 0x100, v240
	s_add_i32 s92, s92, 1
	s_add_i32 s20, s92, 2
	s_min_i32 s20, s20, s80
	s_add_i32 s21, s20, s77
	s_lshl_b32 s21, s21, 6
	s_or_b32 s21, s21, s59
	s_sub_i32 s22, s20, s76
	s_lshl_b32 s22, s22, 5
	s_addk_i32 s22, 0x1000
	s_cmp_lt_i32 s20, s76
	s_cselect_b32 s60, 1, 0
	s_cselect_b32 s20, s21, s22
	s_lshl_b32 s23, s20, 10
	s_add_i32 s23, s23, s81
	s_lshr_b32 s33, s20, 5
	s_lshl_b32 s33, s33, 6
	s_add_i32 s33, s33, s82
	s_waitcnt vmcnt(12)
	v_mfma_f32_16x16x32_bf16 v[188:191], v[176:179], v[156:159], v[212:215]
	v_mfma_f32_16x16x32_bf16 v[192:195], v[168:171], v[156:159], v[242:245]
	v_mfma_f32_16x16x32_bf16 v[188:191], v[172:175], v[160:163], v[188:191]
	v_mfma_f32_16x16x32_bf16 v[192:195], v[164:167], v[160:163], v[192:195]
	ds_read2_b32 v[212:213], v240 offset0:0 offset1:1
	ds_read2_b32 v[214:215], v240 offset0:2 offset1:3
	ds_read2_b32 v[242:243], v240 offset0:4 offset1:5
	ds_read2_b32 v[244:245], v240 offset0:6 offset1:7
	v_mfma_f32_16x16x32_bf16 v[196:199], v[176:179], v[148:151], v[180:183]
	v_mfma_f32_16x16x32_bf16 v[200:203], v[168:171], v[148:151], v[184:187]
	v_mfma_f32_16x16x32_bf16 v[196:199], v[172:175], v[152:155], v[196:199]
	v_mfma_f32_16x16x32_bf16 v[200:203], v[164:167], v[152:155], v[200:203]
	v_exp_f32_e32 v188, v188
	v_exp_f32_e32 v189, v189
	v_exp_f32_e32 v190, v190
	v_exp_f32_e32 v191, v191
	v_exp_f32_e32 v192, v192
	v_exp_f32_e32 v193, v193
	v_exp_f32_e32 v194, v194
	v_exp_f32_e32 v195, v195
	v_cvt_pk_bf16_f32 v246, v188, v189
	v_cvt_pk_bf16_f32 v247, v190, v191
	v_cvt_pk_bf16_f32 v248, v192, v193
	v_cvt_pk_bf16_f32 v249, v194, v195
	v_add_f32_e32 v188, v188, v189
	v_add_f32_e32 v190, v190, v191
	v_add_f32_e32 v192, v192, v193
	v_add_f32_e32 v194, v194, v195
	v_add_f32_e32 v188, v188, v190
	v_add_f32_e32 v192, v192, v194
	v_add_f32_e32 v188, v188, v192
	v_add_f32_e32 v225, v225, v188
	v_mfma_f32_16x16x32_bf16 v[188:191], v[176:179], v[140:143], v[80:83]
	v_mfma_f32_16x16x32_bf16 v[192:195], v[168:171], v[140:143], v[84:87]
	v_mfma_f32_16x16x32_bf16 v[188:191], v[172:175], v[144:147], v[188:191]
	v_mfma_f32_16x16x32_bf16 v[192:195], v[164:167], v[144:147], v[192:195]
	s_waitcnt vmcnt(8)
	v_exp_f32_e32 v196, v196
	v_exp_f32_e32 v197, v197
	v_exp_f32_e32 v198, v198
	v_exp_f32_e32 v199, v199
	v_mfma_f32_16x16x32_bf16 v[112:115], v[32:35], v[246:249], v[112:115]
	v_exp_f32_e32 v200, v200
	v_exp_f32_e32 v201, v201
	v_exp_f32_e32 v202, v202
	v_exp_f32_e32 v203, v203
	v_mfma_f32_16x16x32_bf16 v[108:111], v[28:31], v[246:249], v[108:111]
	v_cvt_pk_bf16_f32 v92, v196, v197
	v_cvt_pk_bf16_f32 v93, v198, v199
	v_cvt_pk_bf16_f32 v94, v200, v201
	v_cvt_pk_bf16_f32 v95, v202, v203
	v_mfma_f32_16x16x32_bf16 v[104:107], v[24:27], v[246:249], v[104:107]
	v_add_f32_e32 v196, v196, v197
	v_add_f32_e32 v198, v198, v199
	v_add_f32_e32 v200, v200, v201
	v_add_f32_e32 v202, v202, v203
	v_mfma_f32_16x16x32_bf16 v[100:103], v[20:23], v[246:249], v[100:103]
	v_add_f32_e32 v196, v196, v198
	v_add_f32_e32 v200, v200, v202
	v_add_f32_e32 v196, v196, v200
	v_add_f32_e32 v224, v224, v196
	v_mfma_f32_16x16x32_bf16 v[196:199], v[176:179], v[132:135], v[204:207]
	v_mfma_f32_16x16x32_bf16 v[200:203], v[168:171], v[132:135], v[208:211]
	v_mfma_f32_16x16x32_bf16 v[196:199], v[172:175], v[136:139], v[196:199]
	v_mfma_f32_16x16x32_bf16 v[200:203], v[164:167], v[136:139], v[200:203]
	buffer_load_dwordx4 v[176:179], v233, s[24:27], s23 offen
	buffer_load_dwordx4 v[172:175], v235, s[24:27], s23 offen
	buffer_load_dwordx4 v[168:171], v1, s[24:27], s23 offen
	buffer_load_dwordx4 v[164:167], v2, s[24:27], s23 offen
	v_exp_f32_e32 v188, v188
	v_exp_f32_e32 v189, v189
	v_exp_f32_e32 v190, v190
	v_exp_f32_e32 v191, v191
	v_mfma_f32_16x16x32_bf16 v[128:131], v[32:35], v[92:95], v[128:131]
	v_exp_f32_e32 v192, v192
	v_exp_f32_e32 v193, v193
	v_exp_f32_e32 v194, v194
	v_exp_f32_e32 v195, v195
	v_mfma_f32_16x16x32_bf16 v[124:127], v[28:31], v[92:95], v[124:127]
	v_cvt_pk_bf16_f32 v246, v188, v189
	v_cvt_pk_bf16_f32 v247, v190, v191
	v_cvt_pk_bf16_f32 v248, v192, v193
	v_cvt_pk_bf16_f32 v249, v194, v195
	v_mfma_f32_16x16x32_bf16 v[120:123], v[24:27], v[92:95], v[120:123]
	v_add_f32_e32 v188, v188, v189
	v_add_f32_e32 v190, v190, v191
	v_add_f32_e32 v192, v192, v193
	v_add_f32_e32 v194, v194, v195
	v_mfma_f32_16x16x32_bf16 v[116:119], v[20:23], v[92:95], v[116:119]
	v_add_f32_e32 v188, v188, v190
	v_add_f32_e32 v192, v192, v194
	v_add_f32_e32 v188, v188, v192
	v_add_f32_e32 v223, v223, v188
	v_exp_f32_e32 v196, v196
	v_exp_f32_e32 v197, v197
	v_exp_f32_e32 v198, v198
	v_exp_f32_e32 v199, v199
	v_mfma_f32_16x16x32_bf16 v[64:67], v[32:35], v[246:249], v[64:67]
	v_exp_f32_e32 v200, v200
	v_exp_f32_e32 v201, v201
	v_exp_f32_e32 v202, v202
	v_exp_f32_e32 v203, v203
	v_mfma_f32_16x16x32_bf16 v[60:63], v[28:31], v[246:249], v[60:63]
	v_cvt_pk_bf16_f32 v92, v196, v197
	v_cvt_pk_bf16_f32 v93, v198, v199
	v_cvt_pk_bf16_f32 v94, v200, v201
	v_cvt_pk_bf16_f32 v95, v202, v203
	v_mfma_f32_16x16x32_bf16 v[56:59], v[24:27], v[246:249], v[56:59]
	v_add_f32_e32 v196, v196, v197
	v_add_f32_e32 v198, v198, v199
	v_add_f32_e32 v200, v200, v201
	v_add_f32_e32 v202, v202, v203
	v_mfma_f32_16x16x32_bf16 v[52:55], v[20:23], v[246:249], v[52:55]
	v_add_f32_e32 v196, v196, v198
	v_add_f32_e32 v200, v200, v202
	v_add_f32_e32 v196, v196, v200
	v_add_f32_e32 v222, v222, v196
	s_waitcnt lgkmcnt(0)
	v_sub_f32_e32 v212, v212, v239
	v_sub_f32_e32 v213, v213, v239
	v_sub_f32_e32 v214, v214, v239
	v_mfma_f32_16x16x32_bf16 v[96:99], v[32:35], v[92:95], v[96:99]
	v_sub_f32_e32 v215, v215, v239
	v_sub_f32_e32 v242, v242, v239
	v_sub_f32_e32 v243, v243, v239
	v_mfma_f32_16x16x32_bf16 v[88:91], v[28:31], v[92:95], v[88:91]
	v_sub_f32_e32 v244, v244, v239
	v_sub_f32_e32 v245, v245, v239
	v_cndmask_b32_e64 v212, v238, v212, s[0:1]
	v_mfma_f32_16x16x32_bf16 v[72:75], v[24:27], v[92:95], v[72:75]
	v_cndmask_b32_e64 v213, v238, v213, s[6:7]
	v_cndmask_b32_e64 v214, v238, v214, s[8:9]
	v_cndmask_b32_e64 v215, v238, v215, s[10:11]
	v_mfma_f32_16x16x32_bf16 v[68:71], v[20:23], v[92:95], v[68:71]
	v_cndmask_b32_e64 v242, v238, v242, s[12:13]
	v_cndmask_b32_e64 v243, v238, v243, s[14:15]
	v_cndmask_b32_e64 v244, v238, v244, s[16:17]
	v_cndmask_b32_e64 v245, v238, v245, s[18:19]
	s_cmp_eq_u32 s60, 0
	s_cbranch_scc1 .Latt_vc5
	buffer_load_dwordx4 v[32:35], v234, s[40:43], s33 offen
	buffer_load_dwordx4 v[28:31], v3, s[40:43], s33 offen
	buffer_load_dwordx4 v[24:27], v220, s[40:43], s33 offen
	buffer_load_dwordx4 v[20:23], v221, s[40:43], s33 offen
	s_branch .Latt_ve5

.Latt_ve5:
	v_add_u32_e32 v240, 0x100, v240
	s_add_i32 s92, s92, 1
	s_add_i32 s20, s92, 2
	s_min_i32 s20, s20, s80
	s_add_i32 s21, s20, s77
	s_lshl_b32 s21, s21, 6
	s_or_b32 s21, s21, s59
	s_sub_i32 s22, s20, s76
	s_lshl_b32 s22, s22, 5
	s_addk_i32 s22, 0x1000
	s_cmp_lt_i32 s20, s76
	s_cselect_b32 s60, 1, 0
	s_cselect_b32 s20, s21, s22
	s_lshl_b32 s23, s20, 10
	s_add_i32 s23, s23, s81
	s_lshr_b32 s33, s20, 5
	s_lshl_b32 s33, s33, 6
	s_add_i32 s33, s33, s82
	s_waitcnt vmcnt(12)
	v_mfma_f32_16x16x32_bf16 v[188:191], v[48:51], v[156:159], v[180:183]
	v_mfma_f32_16x16x32_bf16 v[192:195], v[40:43], v[156:159], v[184:187]
	v_mfma_f32_16x16x32_bf16 v[188:191], v[44:47], v[160:163], v[188:191]
	v_mfma_f32_16x16x32_bf16 v[192:195], v[36:39], v[160:163], v[192:195]
	ds_read2_b32 v[180:181], v240 offset0:0 offset1:1
	ds_read2_b32 v[182:183], v240 offset0:2 offset1:3
	ds_read2_b32 v[184:185], v240 offset0:4 offset1:5
	ds_read2_b32 v[186:187], v240 offset0:6 offset1:7
	v_mfma_f32_16x16x32_bf16 v[196:199], v[48:51], v[148:151], v[80:83]
	v_mfma_f32_16x16x32_bf16 v[200:203], v[40:43], v[148:151], v[84:87]
	v_mfma_f32_16x16x32_bf16 v[196:199], v[44:47], v[152:155], v[196:199]
	v_mfma_f32_16x16x32_bf16 v[200:203], v[36:39], v[152:155], v[200:203]
	v_exp_f32_e32 v188, v188
	v_exp_f32_e32 v189, v189
	v_exp_f32_e32 v190, v190
	v_exp_f32_e32 v191, v191
	v_exp_f32_e32 v192, v192
	v_exp_f32_e32 v193, v193
	v_exp_f32_e32 v194, v194
	v_exp_f32_e32 v195, v195
	v_cvt_pk_bf16_f32 v246, v188, v189
	v_cvt_pk_bf16_f32 v247, v190, v191
	v_cvt_pk_bf16_f32 v248, v192, v193
	v_cvt_pk_bf16_f32 v249, v194, v195
	v_add_f32_e32 v188, v188, v189
	v_add_f32_e32 v190, v190, v191
	v_add_f32_e32 v192, v192, v193
	v_add_f32_e32 v194, v194, v195
	v_add_f32_e32 v188, v188, v190
	v_add_f32_e32 v192, v192, v194
	v_add_f32_e32 v188, v188, v192
	v_add_f32_e32 v225, v225, v188
	v_mfma_f32_16x16x32_bf16 v[188:191], v[48:51], v[140:143], v[204:207]
	v_mfma_f32_16x16x32_bf16 v[192:195], v[40:43], v[140:143], v[208:211]
	v_mfma_f32_16x16x32_bf16 v[188:191], v[44:47], v[144:147], v[188:191]
	v_mfma_f32_16x16x32_bf16 v[192:195], v[36:39], v[144:147], v[192:195]
	s_waitcnt vmcnt(8)
	v_exp_f32_e32 v196, v196
	v_exp_f32_e32 v197, v197
	v_exp_f32_e32 v198, v198
	v_exp_f32_e32 v199, v199
	v_mfma_f32_16x16x32_bf16 v[112:115], v[16:19], v[246:249], v[112:115]
	v_exp_f32_e32 v200, v200
	v_exp_f32_e32 v201, v201
	v_exp_f32_e32 v202, v202
	v_exp_f32_e32 v203, v203
	v_mfma_f32_16x16x32_bf16 v[108:111], v[12:15], v[246:249], v[108:111]
	v_cvt_pk_bf16_f32 v92, v196, v197
	v_cvt_pk_bf16_f32 v93, v198, v199
	v_cvt_pk_bf16_f32 v94, v200, v201
	v_cvt_pk_bf16_f32 v95, v202, v203
	v_mfma_f32_16x16x32_bf16 v[104:107], v[8:11], v[246:249], v[104:107]
	v_add_f32_e32 v196, v196, v197
	v_add_f32_e32 v198, v198, v199
	v_add_f32_e32 v200, v200, v201
	v_add_f32_e32 v202, v202, v203
	v_mfma_f32_16x16x32_bf16 v[100:103], v[4:7], v[246:249], v[100:103]
	v_add_f32_e32 v196, v196, v198
	v_add_f32_e32 v200, v200, v202
	v_add_f32_e32 v196, v196, v200
	v_add_f32_e32 v224, v224, v196
	v_mfma_f32_16x16x32_bf16 v[196:199], v[48:51], v[132:135], v[212:215]
	v_mfma_f32_16x16x32_bf16 v[200:203], v[40:43], v[132:135], v[242:245]
	v_mfma_f32_16x16x32_bf16 v[196:199], v[44:47], v[136:139], v[196:199]
	v_mfma_f32_16x16x32_bf16 v[200:203], v[36:39], v[136:139], v[200:203]
	buffer_load_dwordx4 v[48:51], v233, s[24:27], s23 offen
	buffer_load_dwordx4 v[44:47], v235, s[24:27], s23 offen
	buffer_load_dwordx4 v[40:43], v1, s[24:27], s23 offen
	buffer_load_dwordx4 v[36:39], v2, s[24:27], s23 offen
	v_exp_f32_e32 v188, v188
	v_exp_f32_e32 v189, v189
	v_exp_f32_e32 v190, v190
	v_exp_f32_e32 v191, v191
	v_mfma_f32_16x16x32_bf16 v[128:131], v[16:19], v[92:95], v[128:131]
	v_exp_f32_e32 v192, v192
	v_exp_f32_e32 v193, v193
	v_exp_f32_e32 v194, v194
	v_exp_f32_e32 v195, v195
	v_mfma_f32_16x16x32_bf16 v[124:127], v[12:15], v[92:95], v[124:127]
	v_cvt_pk_bf16_f32 v246, v188, v189
	v_cvt_pk_bf16_f32 v247, v190, v191
	v_cvt_pk_bf16_f32 v248, v192, v193
	v_cvt_pk_bf16_f32 v249, v194, v195
	v_mfma_f32_16x16x32_bf16 v[120:123], v[8:11], v[92:95], v[120:123]
	v_add_f32_e32 v188, v188, v189
	v_add_f32_e32 v190, v190, v191
	v_add_f32_e32 v192, v192, v193
	v_add_f32_e32 v194, v194, v195
	v_mfma_f32_16x16x32_bf16 v[116:119], v[4:7], v[92:95], v[116:119]
	v_add_f32_e32 v188, v188, v190
	v_add_f32_e32 v192, v192, v194
	v_add_f32_e32 v188, v188, v192
	v_add_f32_e32 v223, v223, v188
	v_exp_f32_e32 v196, v196
	v_exp_f32_e32 v197, v197
	v_exp_f32_e32 v198, v198
	v_exp_f32_e32 v199, v199
	v_mfma_f32_16x16x32_bf16 v[64:67], v[16:19], v[246:249], v[64:67]
	v_exp_f32_e32 v200, v200
	v_exp_f32_e32 v201, v201
	v_exp_f32_e32 v202, v202
	v_exp_f32_e32 v203, v203
	v_mfma_f32_16x16x32_bf16 v[60:63], v[12:15], v[246:249], v[60:63]
	v_cvt_pk_bf16_f32 v92, v196, v197
	v_cvt_pk_bf16_f32 v93, v198, v199
	v_cvt_pk_bf16_f32 v94, v200, v201
	v_cvt_pk_bf16_f32 v95, v202, v203
	v_mfma_f32_16x16x32_bf16 v[56:59], v[8:11], v[246:249], v[56:59]
	v_add_f32_e32 v196, v196, v197
	v_add_f32_e32 v198, v198, v199
	v_add_f32_e32 v200, v200, v201
	v_add_f32_e32 v202, v202, v203
	v_mfma_f32_16x16x32_bf16 v[52:55], v[4:7], v[246:249], v[52:55]
	v_add_f32_e32 v196, v196, v198
	v_add_f32_e32 v200, v200, v202
	v_add_f32_e32 v196, v196, v200
	v_add_f32_e32 v222, v222, v196
	s_waitcnt lgkmcnt(0)
	v_sub_f32_e32 v180, v180, v239
	v_sub_f32_e32 v181, v181, v239
	v_sub_f32_e32 v182, v182, v239
	v_mfma_f32_16x16x32_bf16 v[96:99], v[16:19], v[92:95], v[96:99]
	v_sub_f32_e32 v183, v183, v239
	v_sub_f32_e32 v184, v184, v239
	v_sub_f32_e32 v185, v185, v239
	v_mfma_f32_16x16x32_bf16 v[88:91], v[12:15], v[92:95], v[88:91]
	v_sub_f32_e32 v186, v186, v239
	v_sub_f32_e32 v187, v187, v239
	v_cndmask_b32_e64 v180, v238, v180, s[0:1]
	v_mfma_f32_16x16x32_bf16 v[72:75], v[8:11], v[92:95], v[72:75]
	v_cndmask_b32_e64 v181, v238, v181, s[6:7]
	v_cndmask_b32_e64 v182, v238, v182, s[8:9]
	v_cndmask_b32_e64 v183, v238, v183, s[10:11]
	v_mfma_f32_16x16x32_bf16 v[68:71], v[4:7], v[92:95], v[68:71]
	v_cndmask_b32_e64 v184, v238, v184, s[12:13]
	v_cndmask_b32_e64 v185, v238, v185, s[14:15]
	v_cndmask_b32_e64 v186, v238, v186, s[16:17]
	v_cndmask_b32_e64 v187, v238, v187, s[18:19]
	s_cmp_eq_u32 s60, 0
	s_cbranch_scc1 .Latt_vc6
	buffer_load_dwordx4 v[16:19], v234, s[40:43], s33 offen
	buffer_load_dwordx4 v[12:15], v3, s[40:43], s33 offen
	buffer_load_dwordx4 v[8:11], v220, s[40:43], s33 offen
	buffer_load_dwordx4 v[4:7], v221, s[40:43], s33 offen
	s_branch .Latt_ve6

.Latt_ve6:
	v_add_u32_e32 v240, 0x100, v240
	s_add_i32 s92, s92, 1
	s_add_i32 s20, s92, 2
	s_min_i32 s20, s20, s80
	s_add_i32 s21, s20, s77
	s_lshl_b32 s21, s21, 6
	s_or_b32 s21, s21, s59
	s_sub_i32 s22, s20, s76
	s_lshl_b32 s22, s22, 5
	s_addk_i32 s22, 0x1000
	s_cmp_lt_i32 s20, s76
	s_cselect_b32 s60, 1, 0
	s_cselect_b32 s20, s21, s22
	s_lshl_b32 s23, s20, 10
	s_add_i32 s23, s23, s81
	s_lshr_b32 s33, s20, 5
	s_lshl_b32 s33, s33, 6
	s_add_i32 s33, s33, s82
	s_waitcnt vmcnt(12)
	v_mfma_f32_16x16x32_bf16 v[188:191], v[176:179], v[156:159], v[80:83]
	v_mfma_f32_16x16x32_bf16 v[192:195], v[168:171], v[156:159], v[84:87]
	v_mfma_f32_16x16x32_bf16 v[188:191], v[172:175], v[160:163], v[188:191]
	v_mfma_f32_16x16x32_bf16 v[192:195], v[164:167], v[160:163], v[192:195]
	ds_read2_b32 v[80:81], v240 offset0:0 offset1:1
	ds_read2_b32 v[82:83], v240 offset0:2 offset1:3
	ds_read2_b32 v[84:85], v240 offset0:4 offset1:5
	ds_read2_b32 v[86:87], v240 offset0:6 offset1:7
	v_mfma_f32_16x16x32_bf16 v[196:199], v[176:179], v[148:151], v[204:207]
	v_mfma_f32_16x16x32_bf16 v[200:203], v[168:171], v[148:151], v[208:211]
	v_mfma_f32_16x16x32_bf16 v[196:199], v[172:175], v[152:155], v[196:199]
	v_mfma_f32_16x16x32_bf16 v[200:203], v[164:167], v[152:155], v[200:203]
	v_exp_f32_e32 v188, v188
	v_exp_f32_e32 v189, v189
	v_exp_f32_e32 v190, v190
	v_exp_f32_e32 v191, v191
	v_exp_f32_e32 v192, v192
	v_exp_f32_e32 v193, v193
	v_exp_f32_e32 v194, v194
	v_exp_f32_e32 v195, v195
	v_cvt_pk_bf16_f32 v246, v188, v189
	v_cvt_pk_bf16_f32 v247, v190, v191
	v_cvt_pk_bf16_f32 v248, v192, v193
	v_cvt_pk_bf16_f32 v249, v194, v195
	v_add_f32_e32 v188, v188, v189
	v_add_f32_e32 v190, v190, v191
	v_add_f32_e32 v192, v192, v193
	v_add_f32_e32 v194, v194, v195
	v_add_f32_e32 v188, v188, v190
	v_add_f32_e32 v192, v192, v194
	v_add_f32_e32 v188, v188, v192
	v_add_f32_e32 v225, v225, v188
	v_mfma_f32_16x16x32_bf16 v[188:191], v[176:179], v[140:143], v[212:215]
	v_mfma_f32_16x16x32_bf16 v[192:195], v[168:171], v[140:143], v[242:245]
	v_mfma_f32_16x16x32_bf16 v[188:191], v[172:175], v[144:147], v[188:191]
	v_mfma_f32_16x16x32_bf16 v[192:195], v[164:167], v[144:147], v[192:195]
	s_waitcnt vmcnt(8)
	v_exp_f32_e32 v196, v196
	v_exp_f32_e32 v197, v197
	v_exp_f32_e32 v198, v198
	v_exp_f32_e32 v199, v199
	v_mfma_f32_16x16x32_bf16 v[112:115], v[32:35], v[246:249], v[112:115]
	v_exp_f32_e32 v200, v200
	v_exp_f32_e32 v201, v201
	v_exp_f32_e32 v202, v202
	v_exp_f32_e32 v203, v203
	v_mfma_f32_16x16x32_bf16 v[108:111], v[28:31], v[246:249], v[108:111]
	v_cvt_pk_bf16_f32 v92, v196, v197
	v_cvt_pk_bf16_f32 v93, v198, v199
	v_cvt_pk_bf16_f32 v94, v200, v201
	v_cvt_pk_bf16_f32 v95, v202, v203
	v_mfma_f32_16x16x32_bf16 v[104:107], v[24:27], v[246:249], v[104:107]
	v_add_f32_e32 v196, v196, v197
	v_add_f32_e32 v198, v198, v199
	v_add_f32_e32 v200, v200, v201
	v_add_f32_e32 v202, v202, v203
	v_mfma_f32_16x16x32_bf16 v[100:103], v[20:23], v[246:249], v[100:103]
	v_add_f32_e32 v196, v196, v198
	v_add_f32_e32 v200, v200, v202
	v_add_f32_e32 v196, v196, v200
	v_add_f32_e32 v224, v224, v196
	v_mfma_f32_16x16x32_bf16 v[196:199], v[176:179], v[132:135], v[180:183]
	v_mfma_f32_16x16x32_bf16 v[200:203], v[168:171], v[132:135], v[184:187]
	v_mfma_f32_16x16x32_bf16 v[196:199], v[172:175], v[136:139], v[196:199]
	v_mfma_f32_16x16x32_bf16 v[200:203], v[164:167], v[136:139], v[200:203]
	buffer_load_dwordx4 v[176:179], v233, s[24:27], s23 offen
	buffer_load_dwordx4 v[172:175], v235, s[24:27], s23 offen
	buffer_load_dwordx4 v[168:171], v1, s[24:27], s23 offen
	buffer_load_dwordx4 v[164:167], v2, s[24:27], s23 offen
	v_exp_f32_e32 v188, v188
	v_exp_f32_e32 v189, v189
	v_exp_f32_e32 v190, v190
	v_exp_f32_e32 v191, v191
	v_mfma_f32_16x16x32_bf16 v[128:131], v[32:35], v[92:95], v[128:131]
	v_exp_f32_e32 v192, v192
	v_exp_f32_e32 v193, v193
	v_exp_f32_e32 v194, v194
	v_exp_f32_e32 v195, v195
	v_mfma_f32_16x16x32_bf16 v[124:127], v[28:31], v[92:95], v[124:127]
	v_cvt_pk_bf16_f32 v246, v188, v189
	v_cvt_pk_bf16_f32 v247, v190, v191
	v_cvt_pk_bf16_f32 v248, v192, v193
	v_cvt_pk_bf16_f32 v249, v194, v195
	v_mfma_f32_16x16x32_bf16 v[120:123], v[24:27], v[92:95], v[120:123]
	v_add_f32_e32 v188, v188, v189
	v_add_f32_e32 v190, v190, v191
	v_add_f32_e32 v192, v192, v193
	v_add_f32_e32 v194, v194, v195
	v_mfma_f32_16x16x32_bf16 v[116:119], v[20:23], v[92:95], v[116:119]
	v_add_f32_e32 v188, v188, v190
	v_add_f32_e32 v192, v192, v194
	v_add_f32_e32 v188, v188, v192
	v_add_f32_e32 v223, v223, v188
	v_exp_f32_e32 v196, v196
	v_exp_f32_e32 v197, v197
	v_exp_f32_e32 v198, v198
	v_exp_f32_e32 v199, v199
	v_mfma_f32_16x16x32_bf16 v[64:67], v[32:35], v[246:249], v[64:67]
	v_exp_f32_e32 v200, v200
	v_exp_f32_e32 v201, v201
	v_exp_f32_e32 v202, v202
	v_exp_f32_e32 v203, v203
	v_mfma_f32_16x16x32_bf16 v[60:63], v[28:31], v[246:249], v[60:63]
	v_cvt_pk_bf16_f32 v92, v196, v197
	v_cvt_pk_bf16_f32 v93, v198, v199
	v_cvt_pk_bf16_f32 v94, v200, v201
	v_cvt_pk_bf16_f32 v95, v202, v203
	v_mfma_f32_16x16x32_bf16 v[56:59], v[24:27], v[246:249], v[56:59]
	v_add_f32_e32 v196, v196, v197
	v_add_f32_e32 v198, v198, v199
	v_add_f32_e32 v200, v200, v201
	v_add_f32_e32 v202, v202, v203
	v_mfma_f32_16x16x32_bf16 v[52:55], v[20:23], v[246:249], v[52:55]
	v_add_f32_e32 v196, v196, v198
	v_add_f32_e32 v200, v200, v202
	v_add_f32_e32 v196, v196, v200
	v_add_f32_e32 v222, v222, v196
	s_waitcnt lgkmcnt(0)
	v_sub_f32_e32 v80, v80, v239
	v_sub_f32_e32 v81, v81, v239
	v_sub_f32_e32 v82, v82, v239
	v_mfma_f32_16x16x32_bf16 v[96:99], v[32:35], v[92:95], v[96:99]
	v_sub_f32_e32 v83, v83, v239
	v_sub_f32_e32 v84, v84, v239
	v_sub_f32_e32 v85, v85, v239
	v_mfma_f32_16x16x32_bf16 v[88:91], v[28:31], v[92:95], v[88:91]
	v_sub_f32_e32 v86, v86, v239
	v_sub_f32_e32 v87, v87, v239
	v_cndmask_b32_e64 v80, v238, v80, s[0:1]
	v_mfma_f32_16x16x32_bf16 v[72:75], v[24:27], v[92:95], v[72:75]
	v_cndmask_b32_e64 v81, v238, v81, s[6:7]
	v_cndmask_b32_e64 v82, v238, v82, s[8:9]
	v_cndmask_b32_e64 v83, v238, v83, s[10:11]
	v_mfma_f32_16x16x32_bf16 v[68:71], v[20:23], v[92:95], v[68:71]
	v_cndmask_b32_e64 v84, v238, v84, s[12:13]
	v_cndmask_b32_e64 v85, v238, v85, s[14:15]
	v_cndmask_b32_e64 v86, v238, v86, s[16:17]
	v_cndmask_b32_e64 v87, v238, v87, s[18:19]
	s_cmp_eq_u32 s60, 0
	s_cbranch_scc1 .Latt_vc7
	buffer_load_dwordx4 v[32:35], v234, s[40:43], s33 offen
	buffer_load_dwordx4 v[28:31], v3, s[40:43], s33 offen
	buffer_load_dwordx4 v[24:27], v220, s[40:43], s33 offen
	buffer_load_dwordx4 v[20:23], v221, s[40:43], s33 offen
	s_branch .Latt_ve7

.Latt_ve7:
	v_add_u32_e32 v240, 0x100, v240
	s_add_i32 s92, s92, 1
	s_add_i32 s20, s92, 2
	s_min_i32 s20, s20, s80
	s_add_i32 s21, s20, s77
	s_lshl_b32 s21, s21, 6
	s_or_b32 s21, s21, s59
	s_sub_i32 s22, s20, s76
	s_lshl_b32 s22, s22, 5
	s_addk_i32 s22, 0x1000
	s_cmp_lt_i32 s20, s76
	s_cselect_b32 s60, 1, 0
	s_cselect_b32 s20, s21, s22
	s_lshl_b32 s23, s20, 10
	s_add_i32 s23, s23, s81
	s_lshr_b32 s33, s20, 5
	s_lshl_b32 s33, s33, 6
	s_add_i32 s33, s33, s82
	s_waitcnt vmcnt(12)
	v_mfma_f32_16x16x32_bf16 v[188:191], v[48:51], v[156:159], v[204:207]
	v_mfma_f32_16x16x32_bf16 v[192:195], v[40:43], v[156:159], v[208:211]
	v_mfma_f32_16x16x32_bf16 v[188:191], v[44:47], v[160:163], v[188:191]
	v_mfma_f32_16x16x32_bf16 v[192:195], v[36:39], v[160:163], v[192:195]
	v_mfma_f32_16x16x32_bf16 v[196:199], v[48:51], v[148:151], v[212:215]
	v_mfma_f32_16x16x32_bf16 v[200:203], v[40:43], v[148:151], v[242:245]
	v_mfma_f32_16x16x32_bf16 v[196:199], v[44:47], v[152:155], v[196:199]
	v_mfma_f32_16x16x32_bf16 v[200:203], v[36:39], v[152:155], v[200:203]
	s_nop 2
	v_exp_f32_e32 v188, v188
	v_exp_f32_e32 v189, v189
	v_exp_f32_e32 v190, v190
	v_exp_f32_e32 v191, v191
	v_exp_f32_e32 v192, v192
	v_exp_f32_e32 v193, v193
	v_exp_f32_e32 v194, v194
	v_exp_f32_e32 v195, v195
	v_cvt_pk_bf16_f32 v246, v188, v189
	v_cvt_pk_bf16_f32 v247, v190, v191
	v_cvt_pk_bf16_f32 v248, v192, v193
	v_cvt_pk_bf16_f32 v249, v194, v195
	v_add_f32_e32 v188, v188, v189
	v_add_f32_e32 v190, v190, v191
	v_add_f32_e32 v192, v192, v193
	v_add_f32_e32 v194, v194, v195
	v_add_f32_e32 v188, v188, v190
	v_add_f32_e32 v192, v192, v194
	v_add_f32_e32 v188, v188, v192
	v_add_f32_e32 v225, v225, v188
	v_mfma_f32_16x16x32_bf16 v[188:191], v[48:51], v[140:143], v[180:183]
	v_mfma_f32_16x16x32_bf16 v[192:195], v[40:43], v[140:143], v[184:187]
	v_mfma_f32_16x16x32_bf16 v[188:191], v[44:47], v[144:147], v[188:191]
	v_mfma_f32_16x16x32_bf16 v[192:195], v[36:39], v[144:147], v[192:195]
	s_waitcnt vmcnt(8)
	v_exp_f32_e32 v196, v196
	v_exp_f32_e32 v197, v197
	v_exp_f32_e32 v198, v198
	v_exp_f32_e32 v199, v199
	v_mfma_f32_16x16x32_bf16 v[112:115], v[16:19], v[246:249], v[112:115]
	v_exp_f32_e32 v200, v200
	v_exp_f32_e32 v201, v201
	v_exp_f32_e32 v202, v202
	v_exp_f32_e32 v203, v203
	v_mfma_f32_16x16x32_bf16 v[108:111], v[12:15], v[246:249], v[108:111]
	v_cvt_pk_bf16_f32 v92, v196, v197
	v_cvt_pk_bf16_f32 v93, v198, v199
	v_cvt_pk_bf16_f32 v94, v200, v201
	v_cvt_pk_bf16_f32 v95, v202, v203
	v_mfma_f32_16x16x32_bf16 v[104:107], v[8:11], v[246:249], v[104:107]
	v_add_f32_e32 v196, v196, v197
	v_add_f32_e32 v198, v198, v199
	v_add_f32_e32 v200, v200, v201
	v_add_f32_e32 v202, v202, v203
	v_mfma_f32_16x16x32_bf16 v[100:103], v[4:7], v[246:249], v[100:103]
	v_add_f32_e32 v196, v196, v198
	v_add_f32_e32 v200, v200, v202
	v_add_f32_e32 v196, v196, v200
	v_add_f32_e32 v224, v224, v196
	v_mfma_f32_16x16x32_bf16 v[196:199], v[48:51], v[132:135], v[80:83]
	v_mfma_f32_16x16x32_bf16 v[200:203], v[40:43], v[132:135], v[84:87]
	v_mfma_f32_16x16x32_bf16 v[196:199], v[44:47], v[136:139], v[196:199]
	v_mfma_f32_16x16x32_bf16 v[200:203], v[36:39], v[136:139], v[200:203]
	buffer_load_dwordx4 v[48:51], v233, s[24:27], s23 offen
	buffer_load_dwordx4 v[44:47], v235, s[24:27], s23 offen
	buffer_load_dwordx4 v[40:43], v1, s[24:27], s23 offen
	buffer_load_dwordx4 v[36:39], v2, s[24:27], s23 offen
	v_exp_f32_e32 v188, v188
	v_exp_f32_e32 v189, v189
	v_exp_f32_e32 v190, v190
	v_exp_f32_e32 v191, v191
	v_mfma_f32_16x16x32_bf16 v[128:131], v[16:19], v[92:95], v[128:131]
	v_exp_f32_e32 v192, v192
	v_exp_f32_e32 v193, v193
	v_exp_f32_e32 v194, v194
	v_exp_f32_e32 v195, v195
	v_mfma_f32_16x16x32_bf16 v[124:127], v[12:15], v[92:95], v[124:127]
	v_cvt_pk_bf16_f32 v246, v188, v189
	v_cvt_pk_bf16_f32 v247, v190, v191
	v_cvt_pk_bf16_f32 v248, v192, v193
	v_cvt_pk_bf16_f32 v249, v194, v195
	v_mfma_f32_16x16x32_bf16 v[120:123], v[8:11], v[92:95], v[120:123]
	v_add_f32_e32 v188, v188, v189
	v_add_f32_e32 v190, v190, v191
	v_add_f32_e32 v192, v192, v193
	v_add_f32_e32 v194, v194, v195
	v_mfma_f32_16x16x32_bf16 v[116:119], v[4:7], v[92:95], v[116:119]
	v_add_f32_e32 v188, v188, v190
	v_add_f32_e32 v192, v192, v194
	v_add_f32_e32 v188, v188, v192
	v_add_f32_e32 v223, v223, v188
	v_exp_f32_e32 v196, v196
	v_exp_f32_e32 v197, v197
	v_exp_f32_e32 v198, v198
	v_exp_f32_e32 v199, v199
	v_mfma_f32_16x16x32_bf16 v[64:67], v[16:19], v[246:249], v[64:67]
	v_exp_f32_e32 v200, v200
	v_exp_f32_e32 v201, v201
	v_exp_f32_e32 v202, v202
	v_exp_f32_e32 v203, v203
	v_mfma_f32_16x16x32_bf16 v[60:63], v[12:15], v[246:249], v[60:63]
	v_cvt_pk_bf16_f32 v92, v196, v197
	v_cvt_pk_bf16_f32 v93, v198, v199
	v_cvt_pk_bf16_f32 v94, v200, v201
	v_cvt_pk_bf16_f32 v95, v202, v203
	v_mfma_f32_16x16x32_bf16 v[56:59], v[8:11], v[246:249], v[56:59]
	v_add_f32_e32 v196, v196, v197
	v_add_f32_e32 v198, v198, v199
	v_add_f32_e32 v200, v200, v201
	v_add_f32_e32 v202, v202, v203
	v_mfma_f32_16x16x32_bf16 v[52:55], v[4:7], v[246:249], v[52:55]
	v_add_f32_e32 v196, v196, v198
	v_add_f32_e32 v200, v200, v202
	v_add_f32_e32 v196, v196, v200
	v_add_f32_e32 v222, v222, v196
	v_mfma_f32_16x16x32_bf16 v[96:99], v[16:19], v[92:95], v[96:99]
	v_mfma_f32_16x16x32_bf16 v[88:91], v[12:15], v[92:95], v[88:91]
	v_mfma_f32_16x16x32_bf16 v[72:75], v[8:11], v[92:95], v[72:75]
	v_mfma_f32_16x16x32_bf16 v[68:71], v[4:7], v[92:95], v[68:71]
	s_cmp_eq_u32 s60, 0
	s_cbranch_scc1 .Latt_vc8
	buffer_load_dwordx4 v[16:19], v234, s[40:43], s33 offen
	buffer_load_dwordx4 v[12:15], v3, s[40:43], s33 offen
	buffer_load_dwordx4 v[8:11], v220, s[40:43], s33 offen
	buffer_load_dwordx4 v[4:7], v221, s[40:43], s33 offen
	s_branch .Latt_ve8

.Latt_ve8:
	v_add_u32_e32 v240, 0x100, v240
	s_add_i32 s92, s92, 1
	s_add_i32 s20, s92, 2
	s_min_i32 s20, s20, s80
	s_add_i32 s21, s20, s77
	s_lshl_b32 s21, s21, 6
	s_or_b32 s21, s21, s59
	s_sub_i32 s22, s20, s76
	s_lshl_b32 s22, s22, 5
	s_addk_i32 s22, 0x1000
	s_cmp_lt_i32 s20, s76
	s_cselect_b32 s60, 1, 0
	s_cselect_b32 s20, s21, s22
	s_lshl_b32 s23, s20, 10
	s_add_i32 s23, s23, s81
	s_lshr_b32 s33, s20, 5
	s_lshl_b32 s33, s33, 6
	s_add_i32 s33, s33, s82
	s_waitcnt vmcnt(12)
	v_mfma_f32_16x16x32_bf16 v[188:191], v[176:179], v[156:159], v[212:215]
	v_mfma_f32_16x16x32_bf16 v[192:195], v[168:171], v[156:159], v[242:245]
	v_mfma_f32_16x16x32_bf16 v[188:191], v[172:175], v[160:163], v[188:191]
	v_mfma_f32_16x16x32_bf16 v[192:195], v[164:167], v[160:163], v[192:195]
	v_mfma_f32_16x16x32_bf16 v[196:199], v[176:179], v[148:151], v[180:183]
	v_mfma_f32_16x16x32_bf16 v[200:203], v[168:171], v[148:151], v[184:187]
	v_mfma_f32_16x16x32_bf16 v[196:199], v[172:175], v[152:155], v[196:199]
	v_mfma_f32_16x16x32_bf16 v[200:203], v[164:167], v[152:155], v[200:203]
	s_nop 2
	v_exp_f32_e32 v188, v188
	v_exp_f32_e32 v189, v189
	v_exp_f32_e32 v190, v190
	v_exp_f32_e32 v191, v191
	v_exp_f32_e32 v192, v192
	v_exp_f32_e32 v193, v193
	v_exp_f32_e32 v194, v194
	v_exp_f32_e32 v195, v195
	v_cvt_pk_bf16_f32 v246, v188, v189
	v_cvt_pk_bf16_f32 v247, v190, v191
	v_cvt_pk_bf16_f32 v248, v192, v193
	v_cvt_pk_bf16_f32 v249, v194, v195
	v_add_f32_e32 v188, v188, v189
	v_add_f32_e32 v190, v190, v191
	v_add_f32_e32 v192, v192, v193
	v_add_f32_e32 v194, v194, v195
	v_add_f32_e32 v188, v188, v190
	v_add_f32_e32 v192, v192, v194
	v_add_f32_e32 v188, v188, v192
	v_add_f32_e32 v225, v225, v188
	v_mfma_f32_16x16x32_bf16 v[188:191], v[176:179], v[140:143], v[80:83]
	v_mfma_f32_16x16x32_bf16 v[192:195], v[168:171], v[140:143], v[84:87]
	v_mfma_f32_16x16x32_bf16 v[188:191], v[172:175], v[144:147], v[188:191]
	v_mfma_f32_16x16x32_bf16 v[192:195], v[164:167], v[144:147], v[192:195]
	buffer_load_dwordx4 v[176:179], v233, s[24:27], s23 offen
	buffer_load_dwordx4 v[172:175], v235, s[24:27], s23 offen
	buffer_load_dwordx4 v[168:171], v1, s[24:27], s23 offen
	buffer_load_dwordx4 v[164:167], v2, s[24:27], s23 offen
	s_waitcnt vmcnt(12)
	v_exp_f32_e32 v196, v196
	v_exp_f32_e32 v197, v197
	v_exp_f32_e32 v198, v198
	v_exp_f32_e32 v199, v199
	v_mfma_f32_16x16x32_bf16 v[112:115], v[32:35], v[246:249], v[112:115]
	v_exp_f32_e32 v200, v200
	v_exp_f32_e32 v201, v201
	v_exp_f32_e32 v202, v202
	v_exp_f32_e32 v203, v203
	v_mfma_f32_16x16x32_bf16 v[108:111], v[28:31], v[246:249], v[108:111]
	v_cvt_pk_bf16_f32 v92, v196, v197
	v_cvt_pk_bf16_f32 v93, v198, v199
	v_cvt_pk_bf16_f32 v94, v200, v201
	v_cvt_pk_bf16_f32 v95, v202, v203
	v_mfma_f32_16x16x32_bf16 v[104:107], v[24:27], v[246:249], v[104:107]
	v_add_f32_e32 v196, v196, v197
	v_add_f32_e32 v198, v198, v199
	v_add_f32_e32 v200, v200, v201
	v_add_f32_e32 v202, v202, v203
	v_mfma_f32_16x16x32_bf16 v[100:103], v[20:23], v[246:249], v[100:103]
	v_add_f32_e32 v196, v196, v198
	v_add_f32_e32 v200, v200, v202
	v_add_f32_e32 v196, v196, v200
	v_add_f32_e32 v224, v224, v196
	v_exp_f32_e32 v188, v188
	v_exp_f32_e32 v189, v189
	v_exp_f32_e32 v190, v190
	v_exp_f32_e32 v191, v191
	v_mfma_f32_16x16x32_bf16 v[128:131], v[32:35], v[92:95], v[128:131]
	v_exp_f32_e32 v192, v192
	v_exp_f32_e32 v193, v193
	v_exp_f32_e32 v194, v194
	v_exp_f32_e32 v195, v195
	v_mfma_f32_16x16x32_bf16 v[124:127], v[28:31], v[92:95], v[124:127]
	v_cvt_pk_bf16_f32 v246, v188, v189
	v_cvt_pk_bf16_f32 v247, v190, v191
	v_cvt_pk_bf16_f32 v248, v192, v193
	v_cvt_pk_bf16_f32 v249, v194, v195
	v_mfma_f32_16x16x32_bf16 v[120:123], v[24:27], v[92:95], v[120:123]
	v_add_f32_e32 v188, v188, v189
	v_add_f32_e32 v190, v190, v191
	v_add_f32_e32 v192, v192, v193
	v_add_f32_e32 v194, v194, v195
	v_mfma_f32_16x16x32_bf16 v[116:119], v[20:23], v[92:95], v[116:119]
	v_add_f32_e32 v188, v188, v190
	v_add_f32_e32 v192, v192, v194
	v_add_f32_e32 v188, v188, v192
	v_add_f32_e32 v223, v223, v188
	v_mfma_f32_16x16x32_bf16 v[64:67], v[32:35], v[246:249], v[64:67]
	v_mfma_f32_16x16x32_bf16 v[60:63], v[28:31], v[246:249], v[60:63]
	v_mfma_f32_16x16x32_bf16 v[56:59], v[24:27], v[246:249], v[56:59]
	v_mfma_f32_16x16x32_bf16 v[52:55], v[20:23], v[246:249], v[52:55]
	s_cmp_eq_u32 s60, 0
	s_cbranch_scc1 .Latt_vc9
	buffer_load_dwordx4 v[32:35], v234, s[40:43], s33 offen
	buffer_load_dwordx4 v[28:31], v3, s[40:43], s33 offen
	buffer_load_dwordx4 v[24:27], v220, s[40:43], s33 offen
	buffer_load_dwordx4 v[20:23], v221, s[40:43], s33 offen
	s_branch .Latt_ve9

.Latt_ve9:
	v_add_u32_e32 v240, 0x100, v240
	s_add_i32 s92, s92, 1
	s_add_i32 s20, s92, 2
	s_min_i32 s20, s20, s80
	s_add_i32 s21, s20, s77
	s_lshl_b32 s21, s21, 6
	s_or_b32 s21, s21, s59
	s_sub_i32 s22, s20, s76
	s_lshl_b32 s22, s22, 5
	s_addk_i32 s22, 0x1000
	s_cmp_lt_i32 s20, s76
	s_cselect_b32 s60, 1, 0
	s_cselect_b32 s20, s21, s22
	s_lshl_b32 s23, s20, 10
	s_add_i32 s23, s23, s81
	s_lshr_b32 s33, s20, 5
	s_lshl_b32 s33, s33, 6
	s_add_i32 s33, s33, s82
	s_waitcnt vmcnt(12)
	v_mfma_f32_16x16x32_bf16 v[188:191], v[48:51], v[156:159], v[180:183]
	v_mfma_f32_16x16x32_bf16 v[192:195], v[40:43], v[156:159], v[184:187]
	v_mfma_f32_16x16x32_bf16 v[188:191], v[44:47], v[160:163], v[188:191]
	v_mfma_f32_16x16x32_bf16 v[192:195], v[36:39], v[160:163], v[192:195]
	v_mfma_f32_16x16x32_bf16 v[196:199], v[48:51], v[148:151], v[80:83]
	v_mfma_f32_16x16x32_bf16 v[200:203], v[40:43], v[148:151], v[84:87]
	v_mfma_f32_16x16x32_bf16 v[196:199], v[44:47], v[152:155], v[196:199]
	v_mfma_f32_16x16x32_bf16 v[200:203], v[36:39], v[152:155], v[200:203]
	buffer_load_dwordx4 v[48:51], v233, s[24:27], s23 offen
	buffer_load_dwordx4 v[44:47], v235, s[24:27], s23 offen
	buffer_load_dwordx4 v[40:43], v1, s[24:27], s23 offen
	buffer_load_dwordx4 v[36:39], v2, s[24:27], s23 offen
	v_exp_f32_e32 v188, v188
	v_exp_f32_e32 v189, v189
	v_exp_f32_e32 v190, v190
	v_exp_f32_e32 v191, v191
	v_exp_f32_e32 v192, v192
	v_exp_f32_e32 v193, v193
	v_exp_f32_e32 v194, v194
	v_exp_f32_e32 v195, v195
	v_cvt_pk_bf16_f32 v246, v188, v189
	v_cvt_pk_bf16_f32 v247, v190, v191
	v_cvt_pk_bf16_f32 v248, v192, v193
	v_cvt_pk_bf16_f32 v249, v194, v195
	v_add_f32_e32 v188, v188, v189
	v_add_f32_e32 v190, v190, v191
	v_add_f32_e32 v192, v192, v193
	v_add_f32_e32 v194, v194, v195
	v_add_f32_e32 v188, v188, v190
	v_add_f32_e32 v192, v192, v194
	v_add_f32_e32 v188, v188, v192
	v_add_f32_e32 v225, v225, v188
	s_waitcnt vmcnt(12)
	v_exp_f32_e32 v196, v196
	v_exp_f32_e32 v197, v197
	v_exp_f32_e32 v198, v198
	v_exp_f32_e32 v199, v199
	v_mfma_f32_16x16x32_bf16 v[112:115], v[16:19], v[246:249], v[112:115]
	v_exp_f32_e32 v200, v200
	v_exp_f32_e32 v201, v201
	v_exp_f32_e32 v202, v202
	v_exp_f32_e32 v203, v203
	v_mfma_f32_16x16x32_bf16 v[108:111], v[12:15], v[246:249], v[108:111]
	v_cvt_pk_bf16_f32 v92, v196, v197
	v_cvt_pk_bf16_f32 v93, v198, v199
	v_cvt_pk_bf16_f32 v94, v200, v201
	v_cvt_pk_bf16_f32 v95, v202, v203
	v_mfma_f32_16x16x32_bf16 v[104:107], v[8:11], v[246:249], v[104:107]
	v_add_f32_e32 v196, v196, v197
	v_add_f32_e32 v198, v198, v199
	v_add_f32_e32 v200, v200, v201
	v_add_f32_e32 v202, v202, v203
	v_mfma_f32_16x16x32_bf16 v[100:103], v[4:7], v[246:249], v[100:103]
	v_add_f32_e32 v196, v196, v198
	v_add_f32_e32 v200, v200, v202
	v_add_f32_e32 v196, v196, v200
	v_add_f32_e32 v224, v224, v196
	v_mfma_f32_16x16x32_bf16 v[128:131], v[16:19], v[92:95], v[128:131]
	v_mfma_f32_16x16x32_bf16 v[124:127], v[12:15], v[92:95], v[124:127]
	v_mfma_f32_16x16x32_bf16 v[120:123], v[8:11], v[92:95], v[120:123]
	v_mfma_f32_16x16x32_bf16 v[116:119], v[4:7], v[92:95], v[116:119]
	s_cmp_eq_u32 s60, 0
	s_cbranch_scc1 .Latt_vc10
	buffer_load_dwordx4 v[16:19], v234, s[40:43], s33 offen
	buffer_load_dwordx4 v[12:15], v3, s[40:43], s33 offen
	buffer_load_dwordx4 v[8:11], v220, s[40:43], s33 offen
	buffer_load_dwordx4 v[4:7], v221, s[40:43], s33 offen
	s_branch .Latt_ve10

.Latt_ve10:
	v_add_u32_e32 v240, 0x100, v240
	s_add_i32 s92, s92, 1
	s_add_i32 s20, s92, 2
	s_min_i32 s20, s20, s80
	s_add_i32 s21, s20, s77
	s_lshl_b32 s21, s21, 6
	s_or_b32 s21, s21, s59
	s_sub_i32 s22, s20, s76
	s_lshl_b32 s22, s22, 5
	s_addk_i32 s22, 0x1000
	s_cmp_lt_i32 s20, s76
	s_cselect_b32 s60, 1, 0
	s_cselect_b32 s20, s21, s22
	s_lshl_b32 s23, s20, 10
	s_add_i32 s23, s23, s81
	s_lshr_b32 s33, s20, 5
	s_lshl_b32 s33, s33, 6
	s_add_i32 s33, s33, s82
	s_waitcnt vmcnt(12)
	v_mfma_f32_16x16x32_bf16 v[188:191], v[176:179], v[156:159], v[80:83]
	v_mfma_f32_16x16x32_bf16 v[192:195], v[168:171], v[156:159], v[84:87]
	v_mfma_f32_16x16x32_bf16 v[188:191], v[172:175], v[160:163], v[188:191]
	v_mfma_f32_16x16x32_bf16 v[192:195], v[164:167], v[160:163], v[192:195]
	buffer_load_dwordx4 v[176:179], v233, s[24:27], s23 offen
	buffer_load_dwordx4 v[172:175], v235, s[24:27], s23 offen
	buffer_load_dwordx4 v[168:171], v1, s[24:27], s23 offen
	buffer_load_dwordx4 v[164:167], v2, s[24:27], s23 offen
	s_nop 2
	v_exp_f32_e32 v188, v188
	v_exp_f32_e32 v189, v189
	v_exp_f32_e32 v190, v190
	v_exp_f32_e32 v191, v191
	v_exp_f32_e32 v192, v192
	v_exp_f32_e32 v193, v193
	v_exp_f32_e32 v194, v194
	v_exp_f32_e32 v195, v195
	v_cvt_pk_bf16_f32 v246, v188, v189
	v_cvt_pk_bf16_f32 v247, v190, v191
	v_cvt_pk_bf16_f32 v248, v192, v193
	v_cvt_pk_bf16_f32 v249, v194, v195
	v_add_f32_e32 v188, v188, v189
	v_add_f32_e32 v190, v190, v191
	v_add_f32_e32 v192, v192, v193
	v_add_f32_e32 v194, v194, v195
	v_add_f32_e32 v188, v188, v190
	v_add_f32_e32 v192, v192, v194
	v_add_f32_e32 v188, v188, v192
	v_add_f32_e32 v225, v225, v188
	s_waitcnt vmcnt(12)
	v_mfma_f32_16x16x32_bf16 v[112:115], v[32:35], v[246:249], v[112:115]
	v_mfma_f32_16x16x32_bf16 v[108:111], v[28:31], v[246:249], v[108:111]
	v_mfma_f32_16x16x32_bf16 v[104:107], v[24:27], v[246:249], v[104:107]
	v_mfma_f32_16x16x32_bf16 v[100:103], v[20:23], v[246:249], v[100:103]
	s_cmp_eq_u32 s60, 0
	s_cbranch_scc1 .Latt_vc11
	buffer_load_dwordx4 v[32:35], v234, s[40:43], s33 offen
	buffer_load_dwordx4 v[28:31], v3, s[40:43], s33 offen
	buffer_load_dwordx4 v[24:27], v220, s[40:43], s33 offen
	buffer_load_dwordx4 v[20:23], v221, s[40:43], s33 offen
	s_branch .Latt_ve11

.Latt_n8:
	s_mov_b32 s91, 2
.Latt_F0:
	s_add_i32 s20, s92, 2
	s_min_i32 s20, s20, s80
	s_add_i32 s21, s20, s77
	s_lshl_b32 s21, s21, 6
	s_or_b32 s21, s21, s59
	s_sub_i32 s22, s20, s76
	s_lshl_b32 s22, s22, 5
	s_addk_i32 s22, 0x1000
	s_cmp_lt_i32 s20, s76
	s_cselect_b32 s60, 1, 0
	s_cselect_b32 s20, s21, s22
	s_lshl_b32 s23, s20, 10
	s_add_i32 s23, s23, s81
	s_lshr_b32 s33, s20, 5
	s_lshl_b32 s33, s33, 6
	s_add_i32 s33, s33, s82
	s_waitcnt vmcnt(12)
	v_mfma_f32_16x16x32_bf16 v[188:191], v[176:179], v[156:159], v[212:215]
	v_mfma_f32_16x16x32_bf16 v[192:195], v[168:171], v[156:159], v[242:245]
	v_mfma_f32_16x16x32_bf16 v[188:191], v[172:175], v[160:163], v[188:191]
	v_mfma_f32_16x16x32_bf16 v[192:195], v[164:167], v[160:163], v[192:195]
	ds_read2_b32 v[212:213], v240 offset0:0 offset1:1
	ds_read2_b32 v[214:215], v240 offset0:2 offset1:3
	ds_read2_b32 v[242:243], v240 offset0:4 offset1:5
	ds_read2_b32 v[244:245], v240 offset0:6 offset1:7
	v_mfma_f32_16x16x32_bf16 v[196:199], v[176:179], v[148:151], v[180:183]
	v_mfma_f32_16x16x32_bf16 v[200:203], v[168:171], v[148:151], v[184:187]
	v_mfma_f32_16x16x32_bf16 v[196:199], v[172:175], v[152:155], v[196:199]
	v_mfma_f32_16x16x32_bf16 v[200:203], v[164:167], v[152:155], v[200:203]
	v_exp_f32_e32 v188, v188
	v_exp_f32_e32 v189, v189
	v_exp_f32_e32 v190, v190
	v_exp_f32_e32 v191, v191
	v_exp_f32_e32 v192, v192
	v_exp_f32_e32 v193, v193
	v_exp_f32_e32 v194, v194
	v_exp_f32_e32 v195, v195
	v_cvt_pk_bf16_f32 v246, v188, v189
	v_cvt_pk_bf16_f32 v247, v190, v191
	v_cvt_pk_bf16_f32 v248, v192, v193
	v_cvt_pk_bf16_f32 v249, v194, v195
	v_add_f32_e32 v188, v188, v189
	v_add_f32_e32 v190, v190, v191
	v_add_f32_e32 v192, v192, v193
	v_add_f32_e32 v194, v194, v195
	v_add_f32_e32 v188, v188, v190
	v_add_f32_e32 v192, v192, v194
	v_add_f32_e32 v188, v188, v192
	v_add_f32_e32 v225, v225, v188
	v_mfma_f32_16x16x32_bf16 v[188:191], v[176:179], v[140:143], v[80:83]
	v_mfma_f32_16x16x32_bf16 v[192:195], v[168:171], v[140:143], v[84:87]
	v_mfma_f32_16x16x32_bf16 v[188:191], v[172:175], v[144:147], v[188:191]
	v_mfma_f32_16x16x32_bf16 v[192:195], v[164:167], v[144:147], v[192:195]
	s_waitcnt vmcnt(8)
	v_exp_f32_e32 v196, v196
	v_exp_f32_e32 v197, v197
	v_exp_f32_e32 v198, v198
	v_exp_f32_e32 v199, v199
	v_mfma_f32_16x16x32_bf16 v[112:115], v[32:35], v[246:249], v[112:115]
	v_exp_f32_e32 v200, v200
	v_exp_f32_e32 v201, v201
	v_exp_f32_e32 v202, v202
	v_exp_f32_e32 v203, v203
	v_mfma_f32_16x16x32_bf16 v[108:111], v[28:31], v[246:249], v[108:111]
	v_cvt_pk_bf16_f32 v92, v196, v197
	v_cvt_pk_bf16_f32 v93, v198, v199
	v_cvt_pk_bf16_f32 v94, v200, v201
	v_cvt_pk_bf16_f32 v95, v202, v203
	v_mfma_f32_16x16x32_bf16 v[104:107], v[24:27], v[246:249], v[104:107]
	v_add_f32_e32 v196, v196, v197
	v_add_f32_e32 v198, v198, v199
	v_add_f32_e32 v200, v200, v201
	v_add_f32_e32 v202, v202, v203
	v_mfma_f32_16x16x32_bf16 v[100:103], v[20:23], v[246:249], v[100:103]
	v_add_f32_e32 v196, v196, v198
	v_add_f32_e32 v200, v200, v202
	v_add_f32_e32 v196, v196, v200
	v_add_f32_e32 v224, v224, v196
	v_mfma_f32_16x16x32_bf16 v[196:199], v[176:179], v[132:135], v[204:207]
	v_mfma_f32_16x16x32_bf16 v[200:203], v[168:171], v[132:135], v[208:211]
	v_mfma_f32_16x16x32_bf16 v[196:199], v[172:175], v[136:139], v[196:199]
	v_mfma_f32_16x16x32_bf16 v[200:203], v[164:167], v[136:139], v[200:203]
	buffer_load_dwordx4 v[176:179], v233, s[24:27], s23 offen
	buffer_load_dwordx4 v[172:175], v235, s[24:27], s23 offen
	buffer_load_dwordx4 v[168:171], v1, s[24:27], s23 offen
	buffer_load_dwordx4 v[164:167], v2, s[24:27], s23 offen
	v_exp_f32_e32 v188, v188
	v_exp_f32_e32 v189, v189
	v_exp_f32_e32 v190, v190
	v_exp_f32_e32 v191, v191
	v_mfma_f32_16x16x32_bf16 v[128:131], v[32:35], v[92:95], v[128:131]
	v_exp_f32_e32 v192, v192
	v_exp_f32_e32 v193, v193
	v_exp_f32_e32 v194, v194
	v_exp_f32_e32 v195, v195
	v_mfma_f32_16x16x32_bf16 v[124:127], v[28:31], v[92:95], v[124:127]
	v_cvt_pk_bf16_f32 v246, v188, v189
	v_cvt_pk_bf16_f32 v247, v190, v191
	v_cvt_pk_bf16_f32 v248, v192, v193
	v_cvt_pk_bf16_f32 v249, v194, v195
	v_mfma_f32_16x16x32_bf16 v[120:123], v[24:27], v[92:95], v[120:123]
	v_add_f32_e32 v188, v188, v189
	v_add_f32_e32 v190, v190, v191
	v_add_f32_e32 v192, v192, v193
	v_add_f32_e32 v194, v194, v195
	v_mfma_f32_16x16x32_bf16 v[116:119], v[20:23], v[92:95], v[116:119]
	v_add_f32_e32 v188, v188, v190
	v_add_f32_e32 v192, v192, v194
	v_add_f32_e32 v188, v188, v192
	v_add_f32_e32 v223, v223, v188
	v_exp_f32_e32 v196, v196
	v_exp_f32_e32 v197, v197
	v_exp_f32_e32 v198, v198
	v_exp_f32_e32 v199, v199
	v_mfma_f32_16x16x32_bf16 v[64:67], v[32:35], v[246:249], v[64:67]
	v_exp_f32_e32 v200, v200
	v_exp_f32_e32 v201, v201
	v_exp_f32_e32 v202, v202
	v_exp_f32_e32 v203, v203
	v_mfma_f32_16x16x32_bf16 v[60:63], v[28:31], v[246:249], v[60:63]
	v_cvt_pk_bf16_f32 v92, v196, v197
	v_cvt_pk_bf16_f32 v93, v198, v199
	v_cvt_pk_bf16_f32 v94, v200, v201
	v_cvt_pk_bf16_f32 v95, v202, v203
	v_mfma_f32_16x16x32_bf16 v[56:59], v[24:27], v[246:249], v[56:59]
	v_add_f32_e32 v196, v196, v197
	v_add_f32_e32 v198, v198, v199
	v_add_f32_e32 v200, v200, v201
	v_add_f32_e32 v202, v202, v203
	v_mfma_f32_16x16x32_bf16 v[52:55], v[20:23], v[246:249], v[52:55]
	v_add_f32_e32 v196, v196, v198
	v_add_f32_e32 v200, v200, v202
	v_add_f32_e32 v196, v196, v200
	v_add_f32_e32 v222, v222, v196
	s_waitcnt lgkmcnt(0)
	v_sub_f32_e32 v212, v212, v239
	v_sub_f32_e32 v213, v213, v239
	v_sub_f32_e32 v214, v214, v239
	v_mfma_f32_16x16x32_bf16 v[96:99], v[32:35], v[92:95], v[96:99]
	v_sub_f32_e32 v215, v215, v239
	v_sub_f32_e32 v242, v242, v239
	v_sub_f32_e32 v243, v243, v239
	v_mfma_f32_16x16x32_bf16 v[88:91], v[28:31], v[92:95], v[88:91]
	v_sub_f32_e32 v244, v244, v239
	v_sub_f32_e32 v245, v245, v239
	v_cndmask_b32_e64 v212, v238, v212, s[0:1]
	v_mfma_f32_16x16x32_bf16 v[72:75], v[24:27], v[92:95], v[72:75]
	v_cndmask_b32_e64 v213, v238, v213, s[6:7]
	v_cndmask_b32_e64 v214, v238, v214, s[8:9]
	v_cndmask_b32_e64 v215, v238, v215, s[10:11]
	v_mfma_f32_16x16x32_bf16 v[68:71], v[20:23], v[92:95], v[68:71]
	v_cndmask_b32_e64 v242, v238, v242, s[12:13]
	v_cndmask_b32_e64 v243, v238, v243, s[14:15]
	v_cndmask_b32_e64 v244, v238, v244, s[16:17]
	v_cndmask_b32_e64 v245, v238, v245, s[18:19]
	s_cmp_eq_u32 s60, 0
	s_cbranch_scc1 .Latt_vc12
	buffer_load_dwordx4 v[32:35], v234, s[40:43], s33 offen
	buffer_load_dwordx4 v[28:31], v3, s[40:43], s33 offen
	buffer_load_dwordx4 v[24:27], v220, s[40:43], s33 offen
	buffer_load_dwordx4 v[20:23], v221, s[40:43], s33 offen
	s_branch .Latt_ve12

.Latt_ve15:
	v_add_u32_e32 v240, 0x100, v240
	s_add_i32 s92, s92, 1
	s_sub_u32 s91, s91, 1
	s_cmp_lg_u32 s91, 0
	s_cbranch_scc1 .Latt_F0
	s_mov_b32 s91, 8
.Latt_CA:
	s_add_i32 s20, s92, 2
	s_min_i32 s20, s20, s80
	s_add_i32 s21, s20, s77
	s_lshl_b32 s21, s21, 6
	s_or_b32 s21, s21, s59
	s_sub_i32 s22, s20, s76
	s_lshl_b32 s22, s22, 5
	s_addk_i32 s22, 0x1000
	s_cmp_lt_i32 s20, s76
	s_cselect_b32 s60, 1, 0
	s_cselect_b32 s20, s21, s22
	s_lshl_b32 s23, s20, 10
	s_add_i32 s23, s23, s81
	s_lshr_b32 s33, s20, 5
	s_lshl_b32 s33, s33, 6
	s_add_i32 s33, s33, s82
	s_waitcnt vmcnt(12)
	v_mfma_f32_16x16x32_bf16 v[188:191], v[176:179], v[132:135], v[76:79]
	v_mfma_f32_16x16x32_bf16 v[192:195], v[168:171], v[132:135], v[76:79]
	v_mfma_f32_16x16x32_bf16 v[188:191], v[172:175], v[136:139], v[188:191]
	v_mfma_f32_16x16x32_bf16 v[192:195], v[164:167], v[136:139], v[192:195]
	v_mfma_f32_16x16x32_bf16 v[196:199], v[176:179], v[140:143], v[76:79]
	v_mfma_f32_16x16x32_bf16 v[200:203], v[168:171], v[140:143], v[76:79]
	v_mfma_f32_16x16x32_bf16 v[196:199], v[172:175], v[144:147], v[196:199]
	v_mfma_f32_16x16x32_bf16 v[200:203], v[164:167], v[144:147], v[200:203]
	s_nop 2
	v_exp_f32_e32 v188, v188
	v_exp_f32_e32 v189, v189
	v_exp_f32_e32 v190, v190
	v_exp_f32_e32 v191, v191
	v_exp_f32_e32 v192, v192
	v_exp_f32_e32 v193, v193
	v_exp_f32_e32 v194, v194
	v_exp_f32_e32 v195, v195
	v_cvt_pk_bf16_f32 v246, v188, v189
	v_cvt_pk_bf16_f32 v247, v190, v191
	v_cvt_pk_bf16_f32 v248, v192, v193
	v_cvt_pk_bf16_f32 v249, v194, v195
	v_add_f32_e32 v188, v188, v189
	v_add_f32_e32 v190, v190, v191
	v_add_f32_e32 v192, v192, v193
	v_add_f32_e32 v194, v194, v195
	v_add_f32_e32 v188, v188, v190
	v_add_f32_e32 v192, v192, v194
	v_add_f32_e32 v188, v188, v192
	v_add_f32_e32 v222, v222, v188
	v_mfma_f32_16x16x32_bf16 v[188:191], v[176:179], v[148:151], v[76:79]
	v_mfma_f32_16x16x32_bf16 v[192:195], v[168:171], v[148:151], v[76:79]
	v_mfma_f32_16x16x32_bf16 v[188:191], v[172:175], v[152:155], v[188:191]
	v_mfma_f32_16x16x32_bf16 v[192:195], v[164:167], v[152:155], v[192:195]
	s_waitcnt vmcnt(8)
	v_exp_f32_e32 v196, v196
	v_exp_f32_e32 v197, v197
	v_exp_f32_e32 v198, v198
	v_exp_f32_e32 v199, v199
	v_mfma_f32_16x16x32_bf16 v[96:99], v[32:35], v[246:249], v[96:99]
	v_exp_f32_e32 v200, v200
	v_exp_f32_e32 v201, v201
	v_exp_f32_e32 v202, v202
	v_exp_f32_e32 v203, v203
	v_mfma_f32_16x16x32_bf16 v[88:91], v[28:31], v[246:249], v[88:91]
	v_cvt_pk_bf16_f32 v92, v196, v197
	v_cvt_pk_bf16_f32 v93, v198, v199
	v_cvt_pk_bf16_f32 v94, v200, v201
	v_cvt_pk_bf16_f32 v95, v202, v203
	v_mfma_f32_16x16x32_bf16 v[72:75], v[24:27], v[246:249], v[72:75]
	v_add_f32_e32 v196, v196, v197
	v_add_f32_e32 v198, v198, v199
	v_add_f32_e32 v200, v200, v201
	v_add_f32_e32 v202, v202, v203
	v_mfma_f32_16x16x32_bf16 v[68:71], v[20:23], v[246:249], v[68:71]
	v_add_f32_e32 v196, v196, v198
	v_add_f32_e32 v200, v200, v202
	v_add_f32_e32 v196, v196, v200
	v_add_f32_e32 v223, v223, v196
	v_mfma_f32_16x16x32_bf16 v[196:199], v[176:179], v[156:159], v[76:79]
	v_mfma_f32_16x16x32_bf16 v[200:203], v[168:171], v[156:159], v[76:79]
	v_mfma_f32_16x16x32_bf16 v[196:199], v[172:175], v[160:163], v[196:199]
	v_mfma_f32_16x16x32_bf16 v[200:203], v[164:167], v[160:163], v[200:203]
	buffer_load_dwordx4 v[176:179], v233, s[24:27], s23 offen
	buffer_load_dwordx4 v[172:175], v235, s[24:27], s23 offen
	buffer_load_dwordx4 v[168:171], v1, s[24:27], s23 offen
	buffer_load_dwordx4 v[164:167], v2, s[24:27], s23 offen
	v_exp_f32_e32 v188, v188
	v_exp_f32_e32 v189, v189
	v_exp_f32_e32 v190, v190
	v_exp_f32_e32 v191, v191
	v_mfma_f32_16x16x32_bf16 v[64:67], v[32:35], v[92:95], v[64:67]
	v_exp_f32_e32 v192, v192
	v_exp_f32_e32 v193, v193
	v_exp_f32_e32 v194, v194
	v_exp_f32_e32 v195, v195
	v_mfma_f32_16x16x32_bf16 v[60:63], v[28:31], v[92:95], v[60:63]
	v_cvt_pk_bf16_f32 v246, v188, v189
	v_cvt_pk_bf16_f32 v247, v190, v191
	v_cvt_pk_bf16_f32 v248, v192, v193
	v_cvt_pk_bf16_f32 v249, v194, v195
	v_mfma_f32_16x16x32_bf16 v[56:59], v[24:27], v[92:95], v[56:59]
	v_add_f32_e32 v188, v188, v189
	v_add_f32_e32 v190, v190, v191
	v_add_f32_e32 v192, v192, v193
	v_add_f32_e32 v194, v194, v195
	v_mfma_f32_16x16x32_bf16 v[52:55], v[20:23], v[92:95], v[52:55]
	v_add_f32_e32 v188, v188, v190
	v_add_f32_e32 v192, v192, v194
	v_add_f32_e32 v188, v188, v192
	v_add_f32_e32 v224, v224, v188
	v_exp_f32_e32 v196, v196
	v_exp_f32_e32 v197, v197
	v_exp_f32_e32 v198, v198
	v_exp_f32_e32 v199, v199
	v_mfma_f32_16x16x32_bf16 v[128:131], v[32:35], v[246:249], v[128:131]
	v_exp_f32_e32 v200, v200
	v_exp_f32_e32 v201, v201
	v_exp_f32_e32 v202, v202
	v_exp_f32_e32 v203, v203
	v_mfma_f32_16x16x32_bf16 v[124:127], v[28:31], v[246:249], v[124:127]
	v_cvt_pk_bf16_f32 v92, v196, v197
	v_cvt_pk_bf16_f32 v93, v198, v199
	v_cvt_pk_bf16_f32 v94, v200, v201
	v_cvt_pk_bf16_f32 v95, v202, v203
	v_mfma_f32_16x16x32_bf16 v[120:123], v[24:27], v[246:249], v[120:123]
	v_add_f32_e32 v196, v196, v197
	v_add_f32_e32 v198, v198, v199
	v_add_f32_e32 v200, v200, v201
	v_add_f32_e32 v202, v202, v203
	v_mfma_f32_16x16x32_bf16 v[116:119], v[20:23], v[246:249], v[116:119]
	v_add_f32_e32 v196, v196, v198
	v_add_f32_e32 v200, v200, v202
	v_add_f32_e32 v196, v196, v200
	v_add_f32_e32 v225, v225, v196
	v_mfma_f32_16x16x32_bf16 v[112:115], v[32:35], v[92:95], v[112:115]
	v_mfma_f32_16x16x32_bf16 v[108:111], v[28:31], v[92:95], v[108:111]
	v_mfma_f32_16x16x32_bf16 v[104:107], v[24:27], v[92:95], v[104:107]
	v_mfma_f32_16x16x32_bf16 v[100:103], v[20:23], v[92:95], v[100:103]
	s_cmp_eq_u32 s60, 0
	s_cbranch_scc1 .Latt_vc16
	buffer_load_dwordx4 v[32:35], v234, s[40:43], s33 offen
	buffer_load_dwordx4 v[28:31], v3, s[40:43], s33 offen
	buffer_load_dwordx4 v[24:27], v220, s[40:43], s33 offen
	buffer_load_dwordx4 v[20:23], v221, s[40:43], s33 offen
	s_branch .Latt_ve16

.Latt_CB:
	s_add_i32 s20, s92, 2
	s_min_i32 s20, s20, s80
	s_add_i32 s21, s20, s77
	s_lshl_b32 s21, s21, 6
	s_or_b32 s21, s21, s59
	s_sub_i32 s22, s20, s76
	s_lshl_b32 s22, s22, 5
	s_addk_i32 s22, 0x1000
	s_cmp_lt_i32 s20, s76
	s_cselect_b32 s60, 1, 0
	s_cselect_b32 s20, s21, s22
	s_lshl_b32 s23, s20, 10
	s_add_i32 s23, s23, s81
	s_lshr_b32 s33, s20, 5
	s_lshl_b32 s33, s33, 6
	s_add_i32 s33, s33, s82
	s_waitcnt vmcnt(12)
	v_mfma_f32_16x16x32_bf16 v[188:191], v[48:51], v[132:135], v[76:79]
	v_mfma_f32_16x16x32_bf16 v[192:195], v[40:43], v[132:135], v[76:79]
	v_mfma_f32_16x16x32_bf16 v[188:191], v[44:47], v[136:139], v[188:191]
	v_mfma_f32_16x16x32_bf16 v[192:195], v[36:39], v[136:139], v[192:195]
	v_mfma_f32_16x16x32_bf16 v[196:199], v[48:51], v[140:143], v[76:79]
	v_mfma_f32_16x16x32_bf16 v[200:203], v[40:43], v[140:143], v[76:79]
	v_mfma_f32_16x16x32_bf16 v[196:199], v[44:47], v[144:147], v[196:199]
	v_mfma_f32_16x16x32_bf16 v[200:203], v[36:39], v[144:147], v[200:203]
	s_nop 2
	v_exp_f32_e32 v188, v188
	v_exp_f32_e32 v189, v189
	v_exp_f32_e32 v190, v190
	v_exp_f32_e32 v191, v191
	v_exp_f32_e32 v192, v192
	v_exp_f32_e32 v193, v193
	v_exp_f32_e32 v194, v194
	v_exp_f32_e32 v195, v195
	v_cvt_pk_bf16_f32 v246, v188, v189
	v_cvt_pk_bf16_f32 v247, v190, v191
	v_cvt_pk_bf16_f32 v248, v192, v193
	v_cvt_pk_bf16_f32 v249, v194, v195
	v_add_f32_e32 v188, v188, v189
	v_add_f32_e32 v190, v190, v191
	v_add_f32_e32 v192, v192, v193
	v_add_f32_e32 v194, v194, v195
	v_add_f32_e32 v188, v188, v190
	v_add_f32_e32 v192, v192, v194
	v_add_f32_e32 v188, v188, v192
	v_add_f32_e32 v222, v222, v188
	v_mfma_f32_16x16x32_bf16 v[188:191], v[48:51], v[148:151], v[76:79]
	v_mfma_f32_16x16x32_bf16 v[192:195], v[40:43], v[148:151], v[76:79]
	v_mfma_f32_16x16x32_bf16 v[188:191], v[44:47], v[152:155], v[188:191]
	v_mfma_f32_16x16x32_bf16 v[192:195], v[36:39], v[152:155], v[192:195]
	s_waitcnt vmcnt(8)
	v_exp_f32_e32 v196, v196
	v_exp_f32_e32 v197, v197
	v_exp_f32_e32 v198, v198
	v_exp_f32_e32 v199, v199
	v_mfma_f32_16x16x32_bf16 v[96:99], v[16:19], v[246:249], v[96:99]
	v_exp_f32_e32 v200, v200
	v_exp_f32_e32 v201, v201
	v_exp_f32_e32 v202, v202
	v_exp_f32_e32 v203, v203
	v_mfma_f32_16x16x32_bf16 v[88:91], v[12:15], v[246:249], v[88:91]
	v_cvt_pk_bf16_f32 v92, v196, v197
	v_cvt_pk_bf16_f32 v93, v198, v199
	v_cvt_pk_bf16_f32 v94, v200, v201
	v_cvt_pk_bf16_f32 v95, v202, v203
	v_mfma_f32_16x16x32_bf16 v[72:75], v[8:11], v[246:249], v[72:75]
	v_add_f32_e32 v196, v196, v197
	v_add_f32_e32 v198, v198, v199
	v_add_f32_e32 v200, v200, v201
	v_add_f32_e32 v202, v202, v203
	v_mfma_f32_16x16x32_bf16 v[68:71], v[4:7], v[246:249], v[68:71]
	v_add_f32_e32 v196, v196, v198
	v_add_f32_e32 v200, v200, v202
	v_add_f32_e32 v196, v196, v200
	v_add_f32_e32 v223, v223, v196
	v_mfma_f32_16x16x32_bf16 v[196:199], v[48:51], v[156:159], v[76:79]
	v_mfma_f32_16x16x32_bf16 v[200:203], v[40:43], v[156:159], v[76:79]
	v_mfma_f32_16x16x32_bf16 v[196:199], v[44:47], v[160:163], v[196:199]
	v_mfma_f32_16x16x32_bf16 v[200:203], v[36:39], v[160:163], v[200:203]
	buffer_load_dwordx4 v[48:51], v233, s[24:27], s23 offen
	buffer_load_dwordx4 v[44:47], v235, s[24:27], s23 offen
	buffer_load_dwordx4 v[40:43], v1, s[24:27], s23 offen
	buffer_load_dwordx4 v[36:39], v2, s[24:27], s23 offen
	v_exp_f32_e32 v188, v188
	v_exp_f32_e32 v189, v189
	v_exp_f32_e32 v190, v190
	v_exp_f32_e32 v191, v191
	v_mfma_f32_16x16x32_bf16 v[64:67], v[16:19], v[92:95], v[64:67]
	v_exp_f32_e32 v192, v192
	v_exp_f32_e32 v193, v193
	v_exp_f32_e32 v194, v194
	v_exp_f32_e32 v195, v195
	v_mfma_f32_16x16x32_bf16 v[60:63], v[12:15], v[92:95], v[60:63]
	v_cvt_pk_bf16_f32 v246, v188, v189
	v_cvt_pk_bf16_f32 v247, v190, v191
	v_cvt_pk_bf16_f32 v248, v192, v193
	v_cvt_pk_bf16_f32 v249, v194, v195
	v_mfma_f32_16x16x32_bf16 v[56:59], v[8:11], v[92:95], v[56:59]
	v_add_f32_e32 v188, v188, v189
	v_add_f32_e32 v190, v190, v191
	v_add_f32_e32 v192, v192, v193
	v_add_f32_e32 v194, v194, v195
	v_mfma_f32_16x16x32_bf16 v[52:55], v[4:7], v[92:95], v[52:55]
	v_add_f32_e32 v188, v188, v190
	v_add_f32_e32 v192, v192, v194
	v_add_f32_e32 v188, v188, v192
	v_add_f32_e32 v224, v224, v188
	v_exp_f32_e32 v196, v196
	v_exp_f32_e32 v197, v197
	v_exp_f32_e32 v198, v198
	v_exp_f32_e32 v199, v199
	v_mfma_f32_16x16x32_bf16 v[128:131], v[16:19], v[246:249], v[128:131]
	v_exp_f32_e32 v200, v200
	v_exp_f32_e32 v201, v201
	v_exp_f32_e32 v202, v202
	v_exp_f32_e32 v203, v203
	v_mfma_f32_16x16x32_bf16 v[124:127], v[12:15], v[246:249], v[124:127]
	v_cvt_pk_bf16_f32 v92, v196, v197
	v_cvt_pk_bf16_f32 v93, v198, v199
	v_cvt_pk_bf16_f32 v94, v200, v201
	v_cvt_pk_bf16_f32 v95, v202, v203
	v_mfma_f32_16x16x32_bf16 v[120:123], v[8:11], v[246:249], v[120:123]
	v_add_f32_e32 v196, v196, v197
	v_add_f32_e32 v198, v198, v199
	v_add_f32_e32 v200, v200, v201
	v_add_f32_e32 v202, v202, v203
	v_mfma_f32_16x16x32_bf16 v[116:119], v[4:7], v[246:249], v[116:119]
	v_add_f32_e32 v196, v196, v198
	v_add_f32_e32 v200, v200, v202
	v_add_f32_e32 v196, v196, v200
	v_add_f32_e32 v225, v225, v196
	v_mfma_f32_16x16x32_bf16 v[112:115], v[16:19], v[92:95], v[112:115]
	v_mfma_f32_16x16x32_bf16 v[108:111], v[12:15], v[92:95], v[108:111]
	v_mfma_f32_16x16x32_bf16 v[104:107], v[8:11], v[92:95], v[104:107]
	v_mfma_f32_16x16x32_bf16 v[100:103], v[4:7], v[92:95], v[100:103]
	s_cmp_eq_u32 s60, 0
	s_cbranch_scc1 .Latt_vc17
	buffer_load_dwordx4 v[16:19], v234, s[40:43], s33 offen
	buffer_load_dwordx4 v[12:15], v3, s[40:43], s33 offen
	buffer_load_dwordx4 v[8:11], v220, s[40:43], s33 offen
	buffer_load_dwordx4 v[4:7], v221, s[40:43], s33 offen
	s_branch .Latt_ve17
